# MODE-1 second pass: wave-level test selects a copy without the 32 per-element (s > -5e29) compare/select guards
# baseline (speedup 1.0000x reference)
; #define MFMA32(a, b, c) __builtin_amdgcn_mfma_f32_32x32x16_bf16((a), (b), (c), 0, 0, 0)
; DI unsigned pack2(float a, float b) { f32x2_t v = {a, b}; bf16x2_t r = __builtin_convertvector(v, bf16x2_t); return __builtin_bit_cast(unsigned, r); }
; DI float ex2(float x) { return __builtin_amdgcn_exp2f(x); }
; template <int NDT, int MODE, bool ALLON>
; DI void attn_tile(const bf16_t* Kl, int kst, const bf16_t* Vl, const bf16x8 (&q)[4], f32x16 (&O)[NDT], float& m, float& l,
;                   int kbase, int qp, int win, float cbias, const float* tab, bool lane_on) {
;     ...
; #pragma unroll
;     for (int st = 0; st < 2; ++st)
; #pragma unroll
;       for (int i = 0; i < 16; ++i) {
;         const float pe = s[st][i] > -5e29f ? ex2(s[st][i] - mn) : 0.f;
;         psum += pe;
;         s[st][i] = pe;
;       }
;   }
;   l = l * alpha + psum;
;   if (__ballot(alpha != 1.f)) {
; #pragma unroll
;     for (int dt = 0; dt < NDT; ++dt)
; #pragma unroll
;       for (int i = 0; i < 16; ++i) O[dt][i] *= alpha;
;   }
; #pragma unroll
;   for (int st = 0; st < 2; ++st)
; #pragma unroll
;     for (int sk = 0; sk < 2; ++sk) {
;       u32x4 pu;
;       pu[0] = pack2(s[st][8 * sk + 0], s[st][8 * sk + 1]);
;       pu[1] = pack2(s[st][8 * sk + 2], s[st][8 * sk + 3]);
;       pu[2] = pack2(s[st][8 * sk + 4], s[st][8 * sk + 5]);
;       pu[3] = pack2(s[st][8 * sk + 6], s[st][8 * sk + 7]);
;       const bf16x8 pf = __builtin_bit_cast(bf16x8, pu);
; #pragma unroll
;       for (int dt = 0; dt < NDT; ++dt) {
;         const bf16_t* vp = Vl + (dt * 32 + lr) * 72 + st * 32 + sk * 16 + 4 * lh;
;         const uint2 v0 = *(const uint2*)(vp);
;         const uint2 v1 = *(const uint2*)(vp + 8);
;         u32x4 vu; vu[0] = v0.x; vu[1] = v0.y; vu[2] = v1.x; vu[3] = v1.y;
;         O[dt] = MFMA32(__builtin_bit_cast(bf16x8, vu), pf, O[dt]);
;       }
;     }
.LBB0_794:
.LBB0_795:
	v_cmp_gt_f32_e32 vcc, s11, v141
	s_cbranch_vccz .Lm1fast_0
	v_cmp_lt_f32_e32 vcc, s11, v62
	v_sub_f32_e32 v62, v62, v141
	v_exp_f32_e32 v62, v62
	s_nop 0
	v_cndmask_b32_e32 v62, 0, v62, vcc
	v_cmp_lt_f32_e32 vcc, s11, v55
	v_sub_f32_e32 v55, v55, v141
	v_exp_f32_e32 v55, v55
	v_add_f32_e32 v88, 0, v62
	v_cndmask_b32_e32 v55, 0, v55, vcc
	v_cmp_lt_f32_e32 vcc, s11, v61
	v_sub_f32_e32 v61, v61, v141
	v_exp_f32_e32 v61, v61
	v_add_f32_e32 v88, v55, v88
	v_cndmask_b32_e32 v61, 0, v61, vcc
	v_cmp_lt_f32_e32 vcc, s11, v49
	v_sub_f32_e32 v49, v49, v141
	v_exp_f32_e32 v49, v49
	v_add_f32_e32 v88, v61, v88
	v_cndmask_b32_e32 v49, 0, v49, vcc
	v_cmp_lt_f32_e32 vcc, s11, v60
	v_sub_f32_e32 v60, v60, v141
	v_exp_f32_e32 v60, v60
	v_add_f32_e32 v88, v49, v88
	v_cvt_pk_bf16_f32 v49, v61, v49
	v_cndmask_b32_e32 v60, 0, v60, vcc
	v_cmp_lt_f32_e32 vcc, s11, v47
	v_sub_f32_e32 v47, v47, v141
	v_exp_f32_e32 v47, v47
	v_add_f32_e32 v100, v60, v88
	v_cndmask_b32_e32 v88, 0, v47, vcc
	v_cmp_lt_f32_e32 vcc, s11, v59
	v_sub_f32_e32 v59, v59, v141
	v_exp_f32_e32 v59, v59
	v_add_f32_e32 v47, v88, v100
	v_cndmask_b32_e32 v59, 0, v59, vcc
	v_cmp_lt_f32_e32 vcc, s11, v45
	v_sub_f32_e32 v45, v45, v141
	v_exp_f32_e32 v45, v45
	v_add_f32_e32 v47, v59, v47
	v_cndmask_b32_e32 v100, 0, v45, vcc
	v_sub_f32_e32 v45, v58, v141
	v_exp_f32_e32 v45, v45
	v_cmp_lt_f32_e32 vcc, s11, v58
	v_add_f32_e32 v47, v100, v47
	s_nop 0
	v_cndmask_b32_e32 v45, 0, v45, vcc
	v_cmp_lt_f32_e32 vcc, s11, v43
	v_sub_f32_e32 v43, v43, v141
	v_exp_f32_e32 v43, v43
	v_add_f32_e32 v47, v45, v47
	v_cndmask_b32_e32 v43, 0, v43, vcc
	v_add_f32_e32 v58, v43, v47
	v_sub_f32_e32 v47, v57, v141
	v_exp_f32_e32 v47, v47
	v_cmp_lt_f32_e32 vcc, s11, v57
	s_nop 1
	v_cndmask_b32_e32 v47, 0, v47, vcc
	v_cmp_lt_f32_e32 vcc, s11, v42
	v_sub_f32_e32 v42, v42, v141
	v_exp_f32_e32 v42, v42
	v_add_f32_e32 v57, v47, v58
	v_cndmask_b32_e32 v42, 0, v42, vcc
	v_cmp_lt_f32_e32 vcc, s11, v56
	v_sub_f32_e32 v56, v56, v141
	v_exp_f32_e32 v56, v56
	v_add_f32_e32 v57, v42, v57
	v_cndmask_b32_e32 v56, 0, v56, vcc
	v_cmp_lt_f32_e32 vcc, s11, v41
	v_sub_f32_e32 v41, v41, v141
	v_exp_f32_e32 v41, v41
	v_add_f32_e32 v57, v56, v57
	v_cndmask_b32_e32 v41, 0, v41, vcc
	v_cmp_lt_f32_e32 vcc, s11, v54
	v_sub_f32_e32 v54, v54, v141
	v_exp_f32_e32 v54, v54
	v_add_f32_e32 v57, v41, v57
	v_cndmask_b32_e32 v54, 0, v54, vcc
	v_cmp_lt_f32_e32 vcc, s11, v40
	v_sub_f32_e32 v40, v40, v141
	v_exp_f32_e32 v40, v40
	v_add_f32_e32 v57, v54, v57
	v_cndmask_b32_e32 v40, 0, v40, vcc
	v_cmp_lt_f32_e32 vcc, s11, v52
	v_sub_f32_e32 v52, v52, v141
	v_exp_f32_e32 v52, v52
	v_add_f32_e32 v57, v40, v57
	v_cndmask_b32_e32 v52, 0, v52, vcc
	v_cmp_lt_f32_e32 vcc, s11, v39
	v_sub_f32_e32 v39, v39, v141
	v_exp_f32_e32 v39, v39
	v_add_f32_e32 v57, v52, v57
	v_cndmask_b32_e32 v39, 0, v39, vcc
	v_cmp_lt_f32_e32 vcc, s11, v51
	v_sub_f32_e32 v51, v51, v141
	v_exp_f32_e32 v51, v51
	v_add_f32_e32 v57, v39, v57
	v_cndmask_b32_e32 v101, 0, v51, vcc
	v_cmp_lt_f32_e32 vcc, s11, v38
	v_sub_f32_e32 v38, v38, v141
	v_exp_f32_e32 v38, v38
	v_add_f32_e32 v51, v101, v57
	v_cndmask_b32_e32 v38, 0, v38, vcc
	v_cmp_lt_f32_e32 vcc, s11, v48
	v_sub_f32_e32 v48, v48, v141
	v_exp_f32_e32 v48, v48
	v_add_f32_e32 v51, v38, v51
	v_cndmask_b32_e32 v57, 0, v48, vcc
	v_cmp_lt_f32_e32 vcc, s11, v37
	v_sub_f32_e32 v37, v37, v141
	v_exp_f32_e32 v37, v37
	v_add_f32_e32 v48, v57, v51
	v_cvt_pk_bf16_f32 v51, v59, v100
	v_cndmask_b32_e32 v37, 0, v37, vcc
	v_cmp_lt_f32_e32 vcc, s11, v46
	v_sub_f32_e32 v46, v46, v141
	v_exp_f32_e32 v46, v46
	v_add_f32_e32 v48, v37, v48
	v_cndmask_b32_e32 v46, 0, v46, vcc
	v_cmp_lt_f32_e32 vcc, s11, v35
	v_sub_f32_e32 v35, v35, v141
	v_exp_f32_e32 v35, v35
	v_add_f32_e32 v48, v46, v48
	v_cndmask_b32_e32 v102, 0, v35, vcc
	v_cmp_lt_f32_e32 vcc, s11, v44
	v_sub_f32_e32 v44, v44, v141
	v_exp_f32_e32 v44, v44
	v_add_f32_e32 v35, v102, v48
	v_cvt_pk_bf16_f32 v48, v62, v55
	v_cndmask_b32_e32 v44, 0, v44, vcc
	v_cmp_lt_f32_e32 vcc, s11, v36
	v_sub_f32_e32 v36, v36, v141
	v_exp_f32_e32 v36, v36
	v_add_f32_e32 v35, v44, v35
	v_cndmask_b32_e32 v103, 0, v36, vcc
	v_sub_f32_e32 v36, v53, v141
	v_exp_f32_e32 v36, v36
	v_cmp_lt_f32_e32 vcc, s11, v53
	v_add_f32_e32 v35, v103, v35
	s_nop 0
	v_cndmask_b32_e32 v53, 0, v36, vcc
	v_sub_f32_e32 v36, v50, v141
	v_exp_f32_e32 v36, v36
	v_cmp_lt_f32_e32 vcc, s11, v50
	v_add_f32_e32 v35, v53, v35
	v_cvt_pk_bf16_f32 v50, v60, v88
	v_cndmask_b32_e32 v104, 0, v36, vcc
	v_sub_f32_e32 v36, v142, v141
	v_exp_f32_e32 v36, v36
	v_cmp_lt_f32_e32 vcc, s11, v142
	v_add_f32_e32 v35, v104, v35
	s_nop 0
	v_cndmask_b32_e32 v105, 0, v36, vcc
	v_sub_f32_e32 v36, v63, v141
	v_exp_f32_e32 v36, v36
	v_cmp_lt_f32_e32 vcc, s11, v63
	v_add_f32_e32 v35, v105, v35
	s_nop 0
	v_cndmask_b32_e32 v63, 0, v36, vcc
	v_sub_f32_e32 v36, v144, v141
	v_exp_f32_e32 v36, v36
	v_cmp_lt_f32_e32 vcc, s11, v144
	v_add_f32_e32 v35, v63, v35
	s_nop 0
	v_cndmask_b32_e32 v106, 0, v36, vcc
	v_sub_f32_e32 v36, v143, v141
	v_exp_f32_e32 v36, v36
	v_cmp_lt_f32_e32 vcc, s11, v143
	v_add_f32_e32 v35, v106, v35
	s_nop 0
	v_cndmask_b32_e32 v107, 0, v36, vcc
	v_add_f32_e32 v36, v107, v35
	v_fmac_f32_e32 v36, v140, v32
	v_lshlrev_b32_e32 v32, 1, v34
	v_add3_u32 v55, s45, v32, v33
	v_add_u32_e32 v62, 0x2000, v55
	ds_read2_b64 v[32:35], v62 offset0:128 offset1:130
	ds_read2_b64 v[58:61], v62 offset0:132 offset1:134
	v_add_u32_e32 v55, 0x3000, v55
	s_waitcnt lgkmcnt(1)
	v_mfma_f32_32x32x16_bf16 v[160:175], v[32:35], v[48:51], v[160:175]
	ds_read2_b64 v[32:35], v55 offset0:192 offset1:194
	s_waitcnt lgkmcnt(0)
	v_mfma_f32_32x32x16_bf16 v[176:191], v[32:35], v[48:51], v[176:191]
	v_cvt_pk_bf16_f32 v32, v45, v43
	v_cvt_pk_bf16_f32 v33, v47, v42
	v_cvt_pk_bf16_f32 v34, v56, v41
	v_cvt_pk_bf16_f32 v35, v54, v40
	ds_read2_b64 v[40:43], v55 offset0:196 offset1:198
	s_nop 0
	v_mfma_f32_32x32x16_bf16 v[160:175], v[58:61], v[32:35], v[160:175]
	s_waitcnt lgkmcnt(0)
	v_mfma_f32_32x32x16_bf16 v[176:191], v[40:43], v[32:35], v[176:191]
	v_cvt_pk_bf16_f32 v32, v52, v39
	v_cvt_pk_bf16_f32 v33, v101, v38
	ds_read2_b64 v[38:41], v62 offset0:136 offset1:138
	v_cvt_pk_bf16_f32 v34, v57, v37
	v_cvt_pk_bf16_f32 v35, v46, v102
	s_waitcnt lgkmcnt(0)
	s_nop 0
	v_mfma_f32_32x32x16_bf16 v[160:175], v[38:41], v[32:35], v[160:175]
	ds_read2_b64 v[38:41], v55 offset0:200 offset1:202
	s_waitcnt lgkmcnt(0)
	v_mfma_f32_32x32x16_bf16 v[176:191], v[38:41], v[32:35], v[176:191]
	ds_read2_b64 v[38:41], v62 offset0:140 offset1:142
	v_cvt_pk_bf16_f32 v32, v44, v103
	v_cvt_pk_bf16_f32 v33, v53, v104
	v_cvt_pk_bf16_f32 v34, v105, v63
	v_cvt_pk_bf16_f32 v35, v106, v107
	s_waitcnt lgkmcnt(0)
	s_nop 0
	v_mfma_f32_32x32x16_bf16 v[160:175], v[38:41], v[32:35], v[160:175]
	ds_read2_b64 v[38:41], v55 offset0:204 offset1:206
	s_waitcnt lgkmcnt(0)
	v_mfma_f32_32x32x16_bf16 v[176:191], v[38:41], v[32:35], v[176:191]
	s_branch .LBB0_796
; #define MFMA32(a, b, c) __builtin_amdgcn_mfma_f32_32x32x16_bf16((a), (b), (c), 0, 0, 0)
; DI unsigned pack2(float a, float b) { f32x2_t v = {a, b}; bf16x2_t r = __builtin_convertvector(v, bf16x2_t); return __builtin_bit_cast(unsigned, r); }
; DI float ex2(float x) { return __builtin_amdgcn_exp2f(x); }
; template <int NDT, int MODE, bool ALLON>
; DI void attn_tile(const bf16_t* Kl, int kst, const bf16_t* Vl, const bf16x8 (&q)[4], f32x16 (&O)[NDT], float& m, float& l,
;                   int kbase, int qp, int win, float cbias, const float* tab, bool lane_on) {
;     ...
; #pragma unroll
;     for (int st = 0; st < 2; ++st)
; #pragma unroll
;       for (int i = 0; i < 16; ++i) {
;         const float pe = s[st][i] > -5e29f ? ex2(s[st][i] - mn) : 0.f;
;         psum += pe;
;         s[st][i] = pe;
;       }
;   }
;   l = l * alpha + psum;
;   if (__ballot(alpha != 1.f)) {
; #pragma unroll
;     for (int dt = 0; dt < NDT; ++dt)
; #pragma unroll
;       for (int i = 0; i < 16; ++i) O[dt][i] *= alpha;
;   }
; #pragma unroll
;   for (int st = 0; st < 2; ++st)
; #pragma unroll
;     for (int sk = 0; sk < 2; ++sk) {
;       u32x4 pu;
;       pu[0] = pack2(s[st][8 * sk + 0], s[st][8 * sk + 1]);
;       pu[1] = pack2(s[st][8 * sk + 2], s[st][8 * sk + 3]);
;       pu[2] = pack2(s[st][8 * sk + 4], s[st][8 * sk + 5]);
;       pu[3] = pack2(s[st][8 * sk + 6], s[st][8 * sk + 7]);
;       const bf16x8 pf = __builtin_bit_cast(bf16x8, pu);
; #pragma unroll
;       for (int dt = 0; dt < NDT; ++dt) {
;         const bf16_t* vp = Vl + (dt * 32 + lr) * 72 + st * 32 + sk * 16 + 4 * lh;
;         const uint2 v0 = *(const uint2*)(vp);
;         const uint2 v1 = *(const uint2*)(vp + 8);
;         u32x4 vu; vu[0] = v0.x; vu[1] = v0.y; vu[2] = v1.x; vu[3] = v1.y;
;         O[dt] = MFMA32(__builtin_bit_cast(bf16x8, vu), pf, O[dt]);
;       }
;     }
.Lm1fast_0:
	v_sub_f32_e32 v62, v62, v141
	v_exp_f32_e32 v62, v62
	s_nop 0
	v_sub_f32_e32 v55, v55, v141
	v_exp_f32_e32 v55, v55
	v_add_f32_e32 v88, 0, v62
	v_sub_f32_e32 v61, v61, v141
	v_exp_f32_e32 v61, v61
	v_add_f32_e32 v88, v55, v88
	v_sub_f32_e32 v49, v49, v141
	v_exp_f32_e32 v49, v49
	v_add_f32_e32 v88, v61, v88
	v_sub_f32_e32 v60, v60, v141
	v_exp_f32_e32 v60, v60
	v_add_f32_e32 v88, v49, v88
	v_cvt_pk_bf16_f32 v49, v61, v49
	v_sub_f32_e32 v47, v47, v141
	v_exp_f32_e32 v47, v47
	v_add_f32_e32 v100, v60, v88
	v_mov_b32_e32 v88, v47
	v_sub_f32_e32 v59, v59, v141
	v_exp_f32_e32 v59, v59
	v_add_f32_e32 v47, v88, v100
	v_sub_f32_e32 v45, v45, v141
	v_exp_f32_e32 v45, v45
	v_add_f32_e32 v47, v59, v47
	v_mov_b32_e32 v100, v45
	v_sub_f32_e32 v45, v58, v141
	v_exp_f32_e32 v45, v45
	v_add_f32_e32 v47, v100, v47
	s_nop 0
	v_sub_f32_e32 v43, v43, v141
	v_exp_f32_e32 v43, v43
	v_add_f32_e32 v47, v45, v47
	v_add_f32_e32 v58, v43, v47
	v_sub_f32_e32 v47, v57, v141
	v_exp_f32_e32 v47, v47
	s_nop 1
	v_sub_f32_e32 v42, v42, v141
	v_exp_f32_e32 v42, v42
	v_add_f32_e32 v57, v47, v58
	v_sub_f32_e32 v56, v56, v141
	v_exp_f32_e32 v56, v56
	v_add_f32_e32 v57, v42, v57
	v_sub_f32_e32 v41, v41, v141
	v_exp_f32_e32 v41, v41
	v_add_f32_e32 v57, v56, v57
	v_sub_f32_e32 v54, v54, v141
	v_exp_f32_e32 v54, v54
	v_add_f32_e32 v57, v41, v57
	v_sub_f32_e32 v40, v40, v141
	v_exp_f32_e32 v40, v40
	v_add_f32_e32 v57, v54, v57
	v_sub_f32_e32 v52, v52, v141
	v_exp_f32_e32 v52, v52
	v_add_f32_e32 v57, v40, v57
	v_sub_f32_e32 v39, v39, v141
	v_exp_f32_e32 v39, v39
	v_add_f32_e32 v57, v52, v57
	v_sub_f32_e32 v51, v51, v141
	v_exp_f32_e32 v51, v51
	v_add_f32_e32 v57, v39, v57
	v_mov_b32_e32 v101, v51
	v_sub_f32_e32 v38, v38, v141
	v_exp_f32_e32 v38, v38
	v_add_f32_e32 v51, v101, v57
	v_sub_f32_e32 v48, v48, v141
	v_exp_f32_e32 v48, v48
	v_add_f32_e32 v51, v38, v51
	v_mov_b32_e32 v57, v48
	v_sub_f32_e32 v37, v37, v141
	v_exp_f32_e32 v37, v37
	v_add_f32_e32 v48, v57, v51
	v_cvt_pk_bf16_f32 v51, v59, v100
	v_sub_f32_e32 v46, v46, v141
	v_exp_f32_e32 v46, v46
	v_add_f32_e32 v48, v37, v48
	v_sub_f32_e32 v35, v35, v141
	v_exp_f32_e32 v35, v35
	v_add_f32_e32 v48, v46, v48
	v_mov_b32_e32 v102, v35
	v_sub_f32_e32 v44, v44, v141
	v_exp_f32_e32 v44, v44
	v_add_f32_e32 v35, v102, v48
	v_cvt_pk_bf16_f32 v48, v62, v55
	v_sub_f32_e32 v36, v36, v141
	v_exp_f32_e32 v36, v36
	v_add_f32_e32 v35, v44, v35
	v_mov_b32_e32 v103, v36
	v_sub_f32_e32 v36, v53, v141
	v_exp_f32_e32 v36, v36
	v_add_f32_e32 v35, v103, v35
	s_nop 0
	v_mov_b32_e32 v53, v36
	v_sub_f32_e32 v36, v50, v141
	v_exp_f32_e32 v36, v36
	v_add_f32_e32 v35, v53, v35
	v_cvt_pk_bf16_f32 v50, v60, v88
	v_mov_b32_e32 v104, v36
	v_sub_f32_e32 v36, v142, v141
	v_exp_f32_e32 v36, v36
	v_add_f32_e32 v35, v104, v35
	s_nop 0
	v_mov_b32_e32 v105, v36
	v_sub_f32_e32 v36, v63, v141
	v_exp_f32_e32 v36, v36
	v_add_f32_e32 v35, v105, v35
	s_nop 0
	v_mov_b32_e32 v63, v36
	v_sub_f32_e32 v36, v144, v141
	v_exp_f32_e32 v36, v36
	v_add_f32_e32 v35, v63, v35
	s_nop 0
	v_mov_b32_e32 v106, v36
	v_sub_f32_e32 v36, v143, v141
	v_exp_f32_e32 v36, v36
	v_add_f32_e32 v35, v106, v35
	s_nop 0
	v_mov_b32_e32 v107, v36
	v_add_f32_e32 v36, v107, v35
	v_fmac_f32_e32 v36, v140, v32
	v_lshlrev_b32_e32 v32, 1, v34
	v_add3_u32 v55, s45, v32, v33
	v_add_u32_e32 v62, 0x2000, v55
	ds_read2_b64 v[32:35], v62 offset0:128 offset1:130
	ds_read2_b64 v[58:61], v62 offset0:132 offset1:134
	v_add_u32_e32 v55, 0x3000, v55
	s_waitcnt lgkmcnt(1)
	v_mfma_f32_32x32x16_bf16 v[160:175], v[32:35], v[48:51], v[160:175]
	ds_read2_b64 v[32:35], v55 offset0:192 offset1:194
	s_waitcnt lgkmcnt(0)
	v_mfma_f32_32x32x16_bf16 v[176:191], v[32:35], v[48:51], v[176:191]
	v_cvt_pk_bf16_f32 v32, v45, v43
	v_cvt_pk_bf16_f32 v33, v47, v42
	v_cvt_pk_bf16_f32 v34, v56, v41
	v_cvt_pk_bf16_f32 v35, v54, v40
	ds_read2_b64 v[40:43], v55 offset0:196 offset1:198
	s_nop 0
	v_mfma_f32_32x32x16_bf16 v[160:175], v[58:61], v[32:35], v[160:175]
	s_waitcnt lgkmcnt(0)
	v_mfma_f32_32x32x16_bf16 v[176:191], v[40:43], v[32:35], v[176:191]
	v_cvt_pk_bf16_f32 v32, v52, v39
	v_cvt_pk_bf16_f32 v33, v101, v38
	ds_read2_b64 v[38:41], v62 offset0:136 offset1:138
	v_cvt_pk_bf16_f32 v34, v57, v37
	v_cvt_pk_bf16_f32 v35, v46, v102
	s_waitcnt lgkmcnt(0)
	s_nop 0
	v_mfma_f32_32x32x16_bf16 v[160:175], v[38:41], v[32:35], v[160:175]
	ds_read2_b64 v[38:41], v55 offset0:200 offset1:202
	s_waitcnt lgkmcnt(0)
	v_mfma_f32_32x32x16_bf16 v[176:191], v[38:41], v[32:35], v[176:191]
	ds_read2_b64 v[38:41], v62 offset0:140 offset1:142
	v_cvt_pk_bf16_f32 v32, v44, v103
	v_cvt_pk_bf16_f32 v33, v53, v104
	v_cvt_pk_bf16_f32 v34, v105, v63
	v_cvt_pk_bf16_f32 v35, v106, v107
	s_waitcnt lgkmcnt(0)
	s_nop 0
	v_mfma_f32_32x32x16_bf16 v[160:175], v[38:41], v[32:35], v[160:175]
	ds_read2_b64 v[38:41], v55 offset0:204 offset1:206
	s_waitcnt lgkmcnt(0)
	v_mfma_f32_32x32x16_bf16 v[176:191], v[38:41], v[32:35], v[176:191]

; #define MFMA32(a, b, c) __builtin_amdgcn_mfma_f32_32x32x16_bf16((a), (b), (c), 0, 0, 0)
; DI unsigned pack2(float a, float b) { f32x2_t v = {a, b}; bf16x2_t r = __builtin_convertvector(v, bf16x2_t); return __builtin_bit_cast(unsigned, r); }
; DI float ex2(float x) { return __builtin_amdgcn_exp2f(x); }
; template <int NDT, int MODE, bool ALLON>
; DI void attn_tile(const bf16_t* Kl, int kst, const bf16_t* Vl, const bf16x8 (&q)[4], f32x16 (&O)[NDT], float& m, float& l,
;                   int kbase, int qp, int win, float cbias, const float* tab, bool lane_on) {
;     ...
; #pragma unroll
;     for (int st = 0; st < 2; ++st)
; #pragma unroll
;       for (int i = 0; i < 16; ++i) {
;         const float pe = s[st][i] > -5e29f ? ex2(s[st][i] - mn) : 0.f;
;         psum += pe;
;         s[st][i] = pe;
;       }
;   }
;   l = l * alpha + psum;
;   if (__ballot(alpha != 1.f)) {
; #pragma unroll
;     for (int dt = 0; dt < NDT; ++dt)
; #pragma unroll
;       for (int i = 0; i < 16; ++i) O[dt][i] *= alpha;
;   }
; #pragma unroll
;   for (int st = 0; st < 2; ++st)
; #pragma unroll
;     for (int sk = 0; sk < 2; ++sk) {
;       u32x4 pu;
;       pu[0] = pack2(s[st][8 * sk + 0], s[st][8 * sk + 1]);
;       pu[1] = pack2(s[st][8 * sk + 2], s[st][8 * sk + 3]);
;       pu[2] = pack2(s[st][8 * sk + 4], s[st][8 * sk + 5]);
;       pu[3] = pack2(s[st][8 * sk + 6], s[st][8 * sk + 7]);
;       const bf16x8 pf = __builtin_bit_cast(bf16x8, pu);
; #pragma unroll
;       for (int dt = 0; dt < NDT; ++dt) {
;         const bf16_t* vp = Vl + (dt * 32 + lr) * 72 + st * 32 + sk * 16 + 4 * lh;
;         const uint2 v0 = *(const uint2*)(vp);
;         const uint2 v1 = *(const uint2*)(vp + 8);
;         u32x4 vu; vu[0] = v0.x; vu[1] = v0.y; vu[2] = v1.x; vu[3] = v1.y;
;         O[dt] = MFMA32(__builtin_bit_cast(bf16x8, vu), pf, O[dt]);
;       }
.LBB0_878:
.LBB0_879:
	v_cmp_gt_f32_e32 vcc, s11, v130
	s_cbranch_vccz .Lm1fast_1
	v_sub_f32_e32 v88, v134, v130
	v_exp_f32_e32 v88, v88
	v_cmp_lt_f32_e32 vcc, s11, v134
	s_nop 1
	v_cndmask_b32_e32 v88, 0, v88, vcc
	v_cmp_lt_f32_e32 vcc, s11, v63
	v_sub_f32_e32 v63, v63, v130
	v_exp_f32_e32 v63, v63
	v_add_f32_e32 v89, 0, v88
	v_cndmask_b32_e32 v63, 0, v63, vcc
	v_add_f32_e32 v96, v63, v89
	v_sub_f32_e32 v89, v133, v130
	v_exp_f32_e32 v89, v89
	v_cmp_lt_f32_e32 vcc, s11, v133
	s_nop 1
	v_cndmask_b32_e32 v89, 0, v89, vcc
	v_cmp_lt_f32_e32 vcc, s11, v58
	v_sub_f32_e32 v58, v58, v130
	v_exp_f32_e32 v58, v58
	v_add_f32_e32 v96, v89, v96
	v_cndmask_b32_e32 v58, 0, v58, vcc
	v_add_f32_e32 v97, v58, v96
	v_sub_f32_e32 v96, v132, v130
	v_exp_f32_e32 v96, v96
	v_cmp_lt_f32_e32 vcc, s11, v132
	s_nop 1
	v_cndmask_b32_e32 v96, 0, v96, vcc
	v_cmp_lt_f32_e32 vcc, s11, v56
	v_sub_f32_e32 v56, v56, v130
	v_exp_f32_e32 v56, v56
	v_add_f32_e32 v98, v96, v97
	v_cndmask_b32_e32 v97, 0, v56, vcc
	v_cmp_lt_f32_e32 vcc, s11, v62
	v_sub_f32_e32 v62, v62, v130
	v_exp_f32_e32 v62, v62
	v_add_f32_e32 v56, v97, v98
	v_cndmask_b32_e32 v62, 0, v62, vcc
	v_cmp_lt_f32_e32 vcc, s11, v54
	v_sub_f32_e32 v54, v54, v130
	v_exp_f32_e32 v54, v54
	v_add_f32_e32 v56, v62, v56
	v_cndmask_b32_e32 v98, 0, v54, vcc
	v_sub_f32_e32 v54, v60, v130
	v_exp_f32_e32 v54, v54
	v_cmp_lt_f32_e32 vcc, s11, v60
	v_add_f32_e32 v56, v98, v56
	s_nop 0
	v_cndmask_b32_e32 v54, 0, v54, vcc
	v_cmp_lt_f32_e32 vcc, s11, v51
	v_sub_f32_e32 v51, v51, v130
	v_exp_f32_e32 v51, v51
	v_add_f32_e32 v56, v54, v56
	v_cndmask_b32_e32 v51, 0, v51, vcc
	v_add_f32_e32 v60, v51, v56
	v_sub_f32_e32 v56, v57, v130
	v_exp_f32_e32 v56, v56
	v_cmp_lt_f32_e32 vcc, s11, v57
	s_nop 1
	v_cndmask_b32_e32 v56, 0, v56, vcc
	v_cmp_lt_f32_e32 vcc, s11, v48
	v_sub_f32_e32 v48, v48, v130
	v_exp_f32_e32 v48, v48
	v_add_f32_e32 v57, v56, v60
	v_cndmask_b32_e32 v48, 0, v48, vcc
	v_cmp_lt_f32_e32 vcc, s11, v55
	v_sub_f32_e32 v55, v55, v130
	v_exp_f32_e32 v55, v55
	v_add_f32_e32 v57, v48, v57
	v_cndmask_b32_e32 v55, 0, v55, vcc
	v_cmp_lt_f32_e32 vcc, s11, v46
	v_sub_f32_e32 v46, v46, v130
	v_exp_f32_e32 v46, v46
	v_add_f32_e32 v57, v55, v57
	v_cndmask_b32_e32 v46, 0, v46, vcc
	v_cmp_lt_f32_e32 vcc, s11, v52
	v_sub_f32_e32 v52, v52, v130
	v_exp_f32_e32 v52, v52
	v_add_f32_e32 v57, v46, v57
	v_cndmask_b32_e32 v52, 0, v52, vcc
	v_cmp_lt_f32_e32 vcc, s11, v43
	v_sub_f32_e32 v43, v43, v130
	v_exp_f32_e32 v43, v43
	v_add_f32_e32 v57, v52, v57
	v_cndmask_b32_e32 v43, 0, v43, vcc
	v_cmp_lt_f32_e32 vcc, s11, v49
	v_sub_f32_e32 v49, v49, v130
	v_exp_f32_e32 v49, v49
	v_add_f32_e32 v57, v43, v57
	v_cndmask_b32_e32 v49, 0, v49, vcc
	v_cmp_lt_f32_e32 vcc, s11, v40
	v_sub_f32_e32 v40, v40, v130
	v_exp_f32_e32 v40, v40
	v_add_f32_e32 v57, v49, v57
	v_cndmask_b32_e32 v40, 0, v40, vcc
	v_cmp_lt_f32_e32 vcc, s11, v47
	v_sub_f32_e32 v47, v47, v130
	v_exp_f32_e32 v47, v47
	v_add_f32_e32 v57, v40, v57
	v_cndmask_b32_e32 v47, 0, v47, vcc
	v_cmp_lt_f32_e32 vcc, s11, v38
	v_sub_f32_e32 v38, v38, v130
	v_exp_f32_e32 v38, v38
	v_add_f32_e32 v57, v47, v57
	v_cndmask_b32_e32 v100, 0, v38, vcc
	v_cmp_lt_f32_e32 vcc, s11, v45
	v_sub_f32_e32 v45, v45, v130
	v_exp_f32_e32 v45, v45
	v_add_f32_e32 v38, v100, v57
	v_cndmask_b32_e32 v57, 0, v45, vcc
	v_cmp_lt_f32_e32 vcc, s11, v37
	v_sub_f32_e32 v37, v37, v130
	v_exp_f32_e32 v37, v37
	v_add_f32_e32 v38, v57, v38
	v_cndmask_b32_e32 v101, 0, v37, vcc
	v_add_f32_e32 v37, v101, v38
	v_sub_f32_e32 v38, v42, v130
	v_exp_f32_e32 v38, v38
	v_cmp_lt_f32_e32 vcc, s11, v42
	s_nop 1
	v_cndmask_b32_e32 v102, 0, v38, vcc
	v_cmp_lt_f32_e32 vcc, s11, v36
	v_sub_f32_e32 v36, v36, v130
	v_exp_f32_e32 v36, v36
	v_add_f32_e32 v37, v102, v37
	v_cvt_pk_bf16_f32 v38, v96, v97
	v_cndmask_b32_e32 v103, 0, v36, vcc
	v_add_f32_e32 v36, v103, v37
	v_sub_f32_e32 v37, v39, v130
	v_exp_f32_e32 v37, v37
	v_cmp_lt_f32_e32 vcc, s11, v39
	v_cvt_pk_bf16_f32 v39, v62, v98
	s_nop 0
	v_cndmask_b32_e32 v104, 0, v37, vcc
	v_cmp_lt_f32_e32 vcc, s11, v35
	v_sub_f32_e32 v35, v35, v130
	v_exp_f32_e32 v35, v35
	v_add_f32_e32 v36, v104, v36
	v_cvt_pk_bf16_f32 v37, v89, v58
	v_cndmask_b32_e32 v105, 0, v35, vcc
	v_add_f32_e32 v35, v105, v36
	v_sub_f32_e32 v36, v44, v130
	v_exp_f32_e32 v36, v36
	v_cmp_lt_f32_e32 vcc, s11, v44
	s_nop 1
	v_cndmask_b32_e32 v106, 0, v36, vcc
	v_sub_f32_e32 v36, v41, v130
	v_exp_f32_e32 v36, v36
	v_cmp_lt_f32_e32 vcc, s11, v41
	v_add_f32_e32 v35, v106, v35
	s_nop 0
	v_cndmask_b32_e32 v107, 0, v36, vcc
	v_sub_f32_e32 v36, v53, v130
	v_exp_f32_e32 v36, v36
	v_cmp_lt_f32_e32 vcc, s11, v53
	v_add_f32_e32 v35, v107, v35
	s_nop 0
	v_cndmask_b32_e32 v53, 0, v36, vcc
	v_sub_f32_e32 v36, v50, v130
	v_exp_f32_e32 v36, v36
	v_cmp_lt_f32_e32 vcc, s11, v50
	v_add_f32_e32 v35, v53, v35
	s_nop 0
	v_cndmask_b32_e32 v50, 0, v36, vcc
	v_sub_f32_e32 v36, v61, v130
	v_exp_f32_e32 v36, v36
	v_cmp_lt_f32_e32 vcc, s11, v61
	v_add_f32_e32 v35, v50, v35
	s_nop 0
	v_cndmask_b32_e32 v108, 0, v36, vcc
	v_sub_f32_e32 v36, v59, v130
	v_exp_f32_e32 v36, v36
	v_cmp_lt_f32_e32 vcc, s11, v59
	v_add_f32_e32 v35, v108, v35
	s_nop 0
	v_cndmask_b32_e32 v109, 0, v36, vcc
	v_add_f32_e32 v35, v109, v35
	v_fmac_f32_e32 v35, v131, v32
	v_lshlrev_b32_e32 v32, 3, v34
	v_add3_u32 v32, s25, v32, v33
	v_add_u32_e32 v33, 0x2000, v32
	ds_read2_b64 v[58:61], v33 offset0:128 offset1:130
	ds_read2_b64 v[96:99], v33 offset0:132 offset1:134
	v_cvt_pk_bf16_f32 v36, v88, v63
	v_add_u32_e32 v32, 0x3000, v32
	v_mov_b32_e32 v131, v35
	s_waitcnt lgkmcnt(1)
	v_mfma_f32_32x32x16_bf16 v[160:175], v[58:61], v[36:39], v[160:175]
	ds_read2_b64 v[58:61], v32 offset0:192 offset1:194
	s_waitcnt lgkmcnt(0)
	v_mfma_f32_32x32x16_bf16 v[176:191], v[58:61], v[36:39], v[176:191]
	v_cvt_pk_bf16_f32 v39, v52, v43
	ds_read2_b64 v[42:45], v32 offset0:196 offset1:198
	v_cvt_pk_bf16_f32 v36, v54, v51
	v_cvt_pk_bf16_f32 v37, v56, v48
	v_cvt_pk_bf16_f32 v38, v55, v46
	s_nop 1
	v_mfma_f32_32x32x16_bf16 v[160:175], v[96:99], v[36:39], v[160:175]
	s_waitcnt lgkmcnt(0)
	v_mfma_f32_32x32x16_bf16 v[176:191], v[42:45], v[36:39], v[176:191]
	v_cvt_pk_bf16_f32 v36, v49, v40
	ds_read2_b64 v[40:43], v33 offset0:136 offset1:138
	v_cvt_pk_bf16_f32 v37, v47, v100
	v_cvt_pk_bf16_f32 v38, v57, v101
	v_cvt_pk_bf16_f32 v39, v102, v103
	s_waitcnt lgkmcnt(0)
	s_nop 0
	v_mfma_f32_32x32x16_bf16 v[160:175], v[40:43], v[36:39], v[160:175]
	ds_read2_b64 v[40:43], v32 offset0:200 offset1:202
	s_waitcnt lgkmcnt(0)
	v_mfma_f32_32x32x16_bf16 v[176:191], v[40:43], v[36:39], v[176:191]
	ds_read2_b64 v[40:43], v33 offset0:140 offset1:142
	v_cvt_pk_bf16_f32 v36, v104, v105
	v_cvt_pk_bf16_f32 v37, v106, v107
	v_cvt_pk_bf16_f32 v38, v53, v50
	v_cvt_pk_bf16_f32 v39, v108, v109
	s_waitcnt lgkmcnt(0)
	s_nop 0
	v_mfma_f32_32x32x16_bf16 v[160:175], v[40:43], v[36:39], v[160:175]
	ds_read2_b64 v[40:43], v32 offset0:204 offset1:206
	s_waitcnt lgkmcnt(0)
	v_mfma_f32_32x32x16_bf16 v[176:191], v[40:43], v[36:39], v[176:191]
	s_nop 8
	s_branch .LBB0_880
; #define MFMA32(a, b, c) __builtin_amdgcn_mfma_f32_32x32x16_bf16((a), (b), (c), 0, 0, 0)
; DI unsigned pack2(float a, float b) { f32x2_t v = {a, b}; bf16x2_t r = __builtin_convertvector(v, bf16x2_t); return __builtin_bit_cast(unsigned, r); }
; DI float ex2(float x) { return __builtin_amdgcn_exp2f(x); }
; template <int NDT, int MODE, bool ALLON>
; DI void attn_tile(const bf16_t* Kl, int kst, const bf16_t* Vl, const bf16x8 (&q)[4], f32x16 (&O)[NDT], float& m, float& l,
;                   int kbase, int qp, int win, float cbias, const float* tab, bool lane_on) {
;     ...
; #pragma unroll
;     for (int st = 0; st < 2; ++st)
; #pragma unroll
;       for (int i = 0; i < 16; ++i) {
;         const float pe = s[st][i] > -5e29f ? ex2(s[st][i] - mn) : 0.f;
;         psum += pe;
;         s[st][i] = pe;
;       }
;   }
;   l = l * alpha + psum;
;   if (__ballot(alpha != 1.f)) {
; #pragma unroll
;     for (int dt = 0; dt < NDT; ++dt)
; #pragma unroll
;       for (int i = 0; i < 16; ++i) O[dt][i] *= alpha;
;   }
; #pragma unroll
;   for (int st = 0; st < 2; ++st)
; #pragma unroll
;     for (int sk = 0; sk < 2; ++sk) {
;       u32x4 pu;
;       pu[0] = pack2(s[st][8 * sk + 0], s[st][8 * sk + 1]);
;       pu[1] = pack2(s[st][8 * sk + 2], s[st][8 * sk + 3]);
;       pu[2] = pack2(s[st][8 * sk + 4], s[st][8 * sk + 5]);
;       pu[3] = pack2(s[st][8 * sk + 6], s[st][8 * sk + 7]);
;       const bf16x8 pf = __builtin_bit_cast(bf16x8, pu);
; #pragma unroll
;       for (int dt = 0; dt < NDT; ++dt) {
;         const bf16_t* vp = Vl + (dt * 32 + lr) * 72 + st * 32 + sk * 16 + 4 * lh;
;         const uint2 v0 = *(const uint2*)(vp);
;         const uint2 v1 = *(const uint2*)(vp + 8);
;         u32x4 vu; vu[0] = v0.x; vu[1] = v0.y; vu[2] = v1.x; vu[3] = v1.y;
;         O[dt] = MFMA32(__builtin_bit_cast(bf16x8, vu), pf, O[dt]);
;       }
.Lm1fast_1:
	v_sub_f32_e32 v88, v134, v130
	v_exp_f32_e32 v88, v88
	s_nop 1
	v_sub_f32_e32 v63, v63, v130
	v_exp_f32_e32 v63, v63
	v_add_f32_e32 v89, 0, v88
	v_add_f32_e32 v96, v63, v89
	v_sub_f32_e32 v89, v133, v130
	v_exp_f32_e32 v89, v89
	s_nop 1
	v_sub_f32_e32 v58, v58, v130
	v_exp_f32_e32 v58, v58
	v_add_f32_e32 v96, v89, v96
	v_add_f32_e32 v97, v58, v96
	v_sub_f32_e32 v96, v132, v130
	v_exp_f32_e32 v96, v96
	s_nop 1
	v_sub_f32_e32 v56, v56, v130
	v_exp_f32_e32 v56, v56
	v_add_f32_e32 v98, v96, v97
	v_mov_b32_e32 v97, v56
	v_sub_f32_e32 v62, v62, v130
	v_exp_f32_e32 v62, v62
	v_add_f32_e32 v56, v97, v98
	v_sub_f32_e32 v54, v54, v130
	v_exp_f32_e32 v54, v54
	v_add_f32_e32 v56, v62, v56
	v_mov_b32_e32 v98, v54
	v_sub_f32_e32 v54, v60, v130
	v_exp_f32_e32 v54, v54
	v_add_f32_e32 v56, v98, v56
	s_nop 0
	v_sub_f32_e32 v51, v51, v130
	v_exp_f32_e32 v51, v51
	v_add_f32_e32 v56, v54, v56
	v_add_f32_e32 v60, v51, v56
	v_sub_f32_e32 v56, v57, v130
	v_exp_f32_e32 v56, v56
	s_nop 1
	v_sub_f32_e32 v48, v48, v130
	v_exp_f32_e32 v48, v48
	v_add_f32_e32 v57, v56, v60
	v_sub_f32_e32 v55, v55, v130
	v_exp_f32_e32 v55, v55
	v_add_f32_e32 v57, v48, v57
	v_sub_f32_e32 v46, v46, v130
	v_exp_f32_e32 v46, v46
	v_add_f32_e32 v57, v55, v57
	v_sub_f32_e32 v52, v52, v130
	v_exp_f32_e32 v52, v52
	v_add_f32_e32 v57, v46, v57
	v_sub_f32_e32 v43, v43, v130
	v_exp_f32_e32 v43, v43
	v_add_f32_e32 v57, v52, v57
	v_sub_f32_e32 v49, v49, v130
	v_exp_f32_e32 v49, v49
	v_add_f32_e32 v57, v43, v57
	v_sub_f32_e32 v40, v40, v130
	v_exp_f32_e32 v40, v40
	v_add_f32_e32 v57, v49, v57
	v_sub_f32_e32 v47, v47, v130
	v_exp_f32_e32 v47, v47
	v_add_f32_e32 v57, v40, v57
	v_sub_f32_e32 v38, v38, v130
	v_exp_f32_e32 v38, v38
	v_add_f32_e32 v57, v47, v57
	v_mov_b32_e32 v100, v38
	v_sub_f32_e32 v45, v45, v130
	v_exp_f32_e32 v45, v45
	v_add_f32_e32 v38, v100, v57
	v_mov_b32_e32 v57, v45
	v_sub_f32_e32 v37, v37, v130
	v_exp_f32_e32 v37, v37
	v_add_f32_e32 v38, v57, v38
	v_mov_b32_e32 v101, v37
	v_add_f32_e32 v37, v101, v38
	v_sub_f32_e32 v38, v42, v130
	v_exp_f32_e32 v38, v38
	s_nop 1
	v_mov_b32_e32 v102, v38
	v_sub_f32_e32 v36, v36, v130
	v_exp_f32_e32 v36, v36
	v_add_f32_e32 v37, v102, v37
	v_cvt_pk_bf16_f32 v38, v96, v97
	v_mov_b32_e32 v103, v36
	v_add_f32_e32 v36, v103, v37
	v_sub_f32_e32 v37, v39, v130
	v_exp_f32_e32 v37, v37
	v_cvt_pk_bf16_f32 v39, v62, v98
	s_nop 0
	v_mov_b32_e32 v104, v37
	v_sub_f32_e32 v35, v35, v130
	v_exp_f32_e32 v35, v35
	v_add_f32_e32 v36, v104, v36
	v_cvt_pk_bf16_f32 v37, v89, v58
	v_mov_b32_e32 v105, v35
	v_add_f32_e32 v35, v105, v36
	v_sub_f32_e32 v36, v44, v130
	v_exp_f32_e32 v36, v36
	s_nop 1
	v_mov_b32_e32 v106, v36
	v_sub_f32_e32 v36, v41, v130
	v_exp_f32_e32 v36, v36
	v_add_f32_e32 v35, v106, v35
	s_nop 0
	v_mov_b32_e32 v107, v36
	v_sub_f32_e32 v36, v53, v130
	v_exp_f32_e32 v36, v36
	v_add_f32_e32 v35, v107, v35
	s_nop 0
	v_mov_b32_e32 v53, v36
	v_sub_f32_e32 v36, v50, v130
	v_exp_f32_e32 v36, v36
	v_add_f32_e32 v35, v53, v35
	s_nop 0
	v_mov_b32_e32 v50, v36
	v_sub_f32_e32 v36, v61, v130
	v_exp_f32_e32 v36, v36
	v_add_f32_e32 v35, v50, v35
	s_nop 0
	v_mov_b32_e32 v108, v36
	v_sub_f32_e32 v36, v59, v130
	v_exp_f32_e32 v36, v36
	v_add_f32_e32 v35, v108, v35
	s_nop 0
	v_mov_b32_e32 v109, v36
	v_add_f32_e32 v35, v109, v35
	v_fmac_f32_e32 v35, v131, v32
	v_lshlrev_b32_e32 v32, 3, v34
	v_add3_u32 v32, s25, v32, v33
	v_add_u32_e32 v33, 0x2000, v32
	ds_read2_b64 v[58:61], v33 offset0:128 offset1:130
	ds_read2_b64 v[96:99], v33 offset0:132 offset1:134
	v_cvt_pk_bf16_f32 v36, v88, v63
	v_add_u32_e32 v32, 0x3000, v32
	v_mov_b32_e32 v131, v35
	s_waitcnt lgkmcnt(1)
	v_mfma_f32_32x32x16_bf16 v[160:175], v[58:61], v[36:39], v[160:175]
	ds_read2_b64 v[58:61], v32 offset0:192 offset1:194
	s_waitcnt lgkmcnt(0)
	v_mfma_f32_32x32x16_bf16 v[176:191], v[58:61], v[36:39], v[176:191]
	v_cvt_pk_bf16_f32 v39, v52, v43
	ds_read2_b64 v[42:45], v32 offset0:196 offset1:198
	v_cvt_pk_bf16_f32 v36, v54, v51
	v_cvt_pk_bf16_f32 v37, v56, v48
	v_cvt_pk_bf16_f32 v38, v55, v46
	s_nop 1
	v_mfma_f32_32x32x16_bf16 v[160:175], v[96:99], v[36:39], v[160:175]
	s_waitcnt lgkmcnt(0)
	v_mfma_f32_32x32x16_bf16 v[176:191], v[42:45], v[36:39], v[176:191]
	v_cvt_pk_bf16_f32 v36, v49, v40
	ds_read2_b64 v[40:43], v33 offset0:136 offset1:138
	v_cvt_pk_bf16_f32 v37, v47, v100
	v_cvt_pk_bf16_f32 v38, v57, v101
	v_cvt_pk_bf16_f32 v39, v102, v103
	s_waitcnt lgkmcnt(0)
	s_nop 0
	v_mfma_f32_32x32x16_bf16 v[160:175], v[40:43], v[36:39], v[160:175]
	ds_read2_b64 v[40:43], v32 offset0:200 offset1:202
	s_waitcnt lgkmcnt(0)
	v_mfma_f32_32x32x16_bf16 v[176:191], v[40:43], v[36:39], v[176:191]
	ds_read2_b64 v[40:43], v33 offset0:140 offset1:142
	v_cvt_pk_bf16_f32 v36, v104, v105
	v_cvt_pk_bf16_f32 v37, v106, v107
	v_cvt_pk_bf16_f32 v38, v53, v50
	v_cvt_pk_bf16_f32 v39, v108, v109
	s_waitcnt lgkmcnt(0)
	s_nop 0
	v_mfma_f32_32x32x16_bf16 v[160:175], v[40:43], v[36:39], v[160:175]
	ds_read2_b64 v[40:43], v32 offset0:204 offset1:206
	s_waitcnt lgkmcnt(0)
	v_mfma_f32_32x32x16_bf16 v[176:191], v[40:43], v[36:39], v[176:191]
	s_nop 8

; #define MFMA32(a, b, c) __builtin_amdgcn_mfma_f32_32x32x16_bf16((a), (b), (c), 0, 0, 0)
; DI unsigned pack2(float a, float b) { f32x2_t v = {a, b}; bf16x2_t r = __builtin_convertvector(v, bf16x2_t); return __builtin_bit_cast(unsigned, r); }
; DI float ex2(float x) { return __builtin_amdgcn_exp2f(x); }
; template <int NDT, int MODE, bool ALLON>
; DI void attn_tile(const bf16_t* Kl, int kst, const bf16_t* Vl, const bf16x8 (&q)[4], f32x16 (&O)[NDT], float& m, float& l,
;                   int kbase, int qp, int win, float cbias, const float* tab, bool lane_on) {
;     ...
; #pragma unroll
;     for (int st = 0; st < 2; ++st)
; #pragma unroll
;       for (int i = 0; i < 16; ++i) {
;         const float pe = s[st][i] > -5e29f ? ex2(s[st][i] - mn) : 0.f;
;         psum += pe;
;         s[st][i] = pe;
;       }
;   }
;   l = l * alpha + psum;
;   if (__ballot(alpha != 1.f)) {
; #pragma unroll
;     for (int dt = 0; dt < NDT; ++dt)
; #pragma unroll
;       for (int i = 0; i < 16; ++i) O[dt][i] *= alpha;
;   }
; #pragma unroll
;   for (int st = 0; st < 2; ++st)
; #pragma unroll
;     for (int sk = 0; sk < 2; ++sk) {
;       u32x4 pu;
;       pu[0] = pack2(s[st][8 * sk + 0], s[st][8 * sk + 1]);
;       pu[1] = pack2(s[st][8 * sk + 2], s[st][8 * sk + 3]);
;       pu[2] = pack2(s[st][8 * sk + 4], s[st][8 * sk + 5]);
;       pu[3] = pack2(s[st][8 * sk + 6], s[st][8 * sk + 7]);
;       const bf16x8 pf = __builtin_bit_cast(bf16x8, pu);
; #pragma unroll
;       for (int dt = 0; dt < NDT; ++dt) {
;         const bf16_t* vp = Vl + (dt * 32 + lr) * 72 + st * 32 + sk * 16 + 4 * lh;
;         const uint2 v0 = *(const uint2*)(vp);
;         const uint2 v1 = *(const uint2*)(vp + 8);
;         u32x4 vu; vu[0] = v0.x; vu[1] = v0.y; vu[2] = v1.x; vu[3] = v1.y;
;         O[dt] = MFMA32(__builtin_bit_cast(bf16x8, vu), pf, O[dt]);
;       }
.LBB0_898:
	v_cmp_gt_f32_e32 vcc, s11, v101
	s_cbranch_vccz .Lm1fast_2
	v_sub_f32_e32 v58, v133, v101
	v_exp_f32_e32 v58, v58
	v_sub_f32_e32 v59, v131, v101
	v_exp_f32_e32 v59, v59
	v_cmp_lt_f32_e32 vcc, s11, v133
	v_sub_f32_e32 v62, v128, v101
	v_exp_f32_e32 v62, v62
	v_cndmask_b32_e32 v58, 0, v58, vcc
	v_cmp_lt_f32_e32 vcc, s11, v131
	v_add_f32_e32 v60, 0, v58
	v_sub_f32_e32 v63, v130, v101
	v_cndmask_b32_e32 v59, 0, v59, vcc
	v_add_f32_e32 v61, v59, v60
	v_sub_f32_e32 v60, v132, v101
	v_exp_f32_e32 v60, v60
	v_exp_f32_e32 v63, v63
	v_cmp_lt_f32_e32 vcc, s11, v132
	v_sub_f32_e32 v77, v115, v101
	v_exp_f32_e32 v77, v77
	v_cndmask_b32_e32 v60, 0, v60, vcc
	v_cmp_lt_f32_e32 vcc, s11, v128
	v_add_f32_e32 v61, v60, v61
	v_lshlrev_b32_e32 v80, 1, v100
	v_cndmask_b32_e32 v62, 0, v62, vcc
	v_cmp_lt_f32_e32 vcc, s11, v130
	v_add_f32_e32 v61, v62, v61
	s_nop 0
	v_cndmask_b32_e32 v64, 0, v63, vcc
	v_sub_f32_e32 v63, v126, v101
	v_exp_f32_e32 v63, v63
	v_cmp_lt_f32_e32 vcc, s11, v126
	v_add_f32_e32 v61, v64, v61
	s_nop 0
	v_cndmask_b32_e32 v66, 0, v63, vcc
	v_sub_f32_e32 v63, v129, v101
	v_exp_f32_e32 v63, v63
	v_cmp_lt_f32_e32 vcc, s11, v129
	v_add_f32_e32 v61, v66, v61
	v_cvt_pk_bf16_f32 v78, v64, v66
	v_cndmask_b32_e32 v68, 0, v63, vcc
	v_sub_f32_e32 v63, v124, v101
	v_exp_f32_e32 v63, v63
	v_cmp_lt_f32_e32 vcc, s11, v124
	v_add_f32_e32 v61, v68, v61
	s_nop 0
	v_cndmask_b32_e32 v70, 0, v63, vcc
	v_add_f32_e32 v63, v70, v61
	v_sub_f32_e32 v61, v127, v101
	v_exp_f32_e32 v61, v61
	v_cmp_lt_f32_e32 vcc, s11, v127
	v_cvt_pk_bf16_f32 v79, v68, v70
	s_nop 0
	v_cndmask_b32_e32 v61, 0, v61, vcc
	v_add_f32_e32 v65, v61, v63
	v_sub_f32_e32 v63, v122, v101
	v_exp_f32_e32 v63, v63
	v_cmp_lt_f32_e32 vcc, s11, v122
	s_nop 1
	v_cndmask_b32_e32 v63, 0, v63, vcc
	v_add_f32_e32 v67, v63, v65
	v_sub_f32_e32 v65, v125, v101
	v_exp_f32_e32 v65, v65
	v_cmp_lt_f32_e32 vcc, s11, v125
	s_nop 1
	v_cndmask_b32_e32 v65, 0, v65, vcc
	v_add_f32_e32 v69, v65, v67
	v_sub_f32_e32 v67, v120, v101
	v_exp_f32_e32 v67, v67
	v_cmp_lt_f32_e32 vcc, s11, v120
	s_nop 1
	v_cndmask_b32_e32 v67, 0, v67, vcc
	v_add_f32_e32 v71, v67, v69
	v_sub_f32_e32 v69, v123, v101
	v_exp_f32_e32 v69, v69
	v_cmp_lt_f32_e32 vcc, s11, v123
	s_nop 1
	v_cndmask_b32_e32 v69, 0, v69, vcc
	v_add_f32_e32 v72, v69, v71
	v_sub_f32_e32 v71, v116, v101
	v_exp_f32_e32 v71, v71
	v_cmp_lt_f32_e32 vcc, s11, v116
	s_nop 1
	v_cndmask_b32_e32 v71, 0, v71, vcc
	v_add_f32_e32 v73, v71, v72
	v_sub_f32_e32 v72, v121, v101
	v_exp_f32_e32 v72, v72
	v_cmp_lt_f32_e32 vcc, s11, v121
	s_nop 1
	v_cndmask_b32_e32 v72, 0, v72, vcc
	v_add_f32_e32 v74, v72, v73
	v_sub_f32_e32 v73, v114, v101
	v_exp_f32_e32 v73, v73
	v_cmp_lt_f32_e32 vcc, s11, v114
	s_nop 1
	v_cndmask_b32_e32 v73, 0, v73, vcc
	v_add_f32_e32 v75, v73, v74
	v_sub_f32_e32 v74, v118, v101
	v_exp_f32_e32 v74, v74
	v_cmp_lt_f32_e32 vcc, s11, v118
	s_nop 1
	v_cndmask_b32_e32 v74, 0, v74, vcc
	v_add_f32_e32 v76, v74, v75
	v_sub_f32_e32 v75, v110, v101
	v_exp_f32_e32 v75, v75
	v_cmp_lt_f32_e32 vcc, s11, v110
	s_nop 1
	v_cndmask_b32_e32 v75, 0, v75, vcc
	v_cmp_lt_f32_e32 vcc, s11, v115
	v_add_f32_e32 v76, v75, v76
	s_nop 0
	v_cndmask_b32_e32 v88, 0, v77, vcc
	v_sub_f32_e32 v77, v108, v101
	v_exp_f32_e32 v77, v77
	v_cmp_lt_f32_e32 vcc, s11, v108
	v_add_f32_e32 v76, v88, v76
	s_nop 0
	v_cndmask_b32_e32 v89, 0, v77, vcc
	v_sub_f32_e32 v77, v112, v101
	v_exp_f32_e32 v77, v77
	v_cmp_lt_f32_e32 vcc, s11, v112
	v_add_f32_e32 v76, v89, v76
	s_nop 0
	v_cndmask_b32_e32 v108, 0, v77, vcc
	v_sub_f32_e32 v77, v104, v101
	v_exp_f32_e32 v77, v77
	v_cmp_lt_f32_e32 vcc, s11, v104
	v_add_f32_e32 v76, v108, v76
	s_nop 0
	v_cndmask_b32_e32 v104, 0, v77, vcc
	v_sub_f32_e32 v77, v109, v101
	v_exp_f32_e32 v77, v77
	v_cmp_lt_f32_e32 vcc, s11, v109
	v_add_f32_e32 v76, v104, v76
	s_nop 0
	v_cndmask_b32_e32 v109, 0, v77, vcc
	v_sub_f32_e32 v77, v103, v101
	v_exp_f32_e32 v77, v77
	v_cmp_lt_f32_e32 vcc, s11, v103
	v_add_f32_e32 v76, v109, v76
	s_nop 0
	v_cndmask_b32_e32 v103, 0, v77, vcc
	v_sub_f32_e32 v77, v105, v101
	v_exp_f32_e32 v77, v77
	v_cmp_lt_f32_e32 vcc, s11, v105
	v_add_f32_e32 v76, v103, v76
	s_nop 0
	v_cndmask_b32_e32 v105, 0, v77, vcc
	v_sub_f32_e32 v77, v102, v101
	v_exp_f32_e32 v77, v77
	v_cmp_lt_f32_e32 vcc, s11, v102
	v_add_f32_e32 v76, v105, v76
	s_nop 0
	v_cndmask_b32_e32 v110, 0, v77, vcc
	v_sub_f32_e32 v77, v107, v101
	v_exp_f32_e32 v77, v77
	v_cmp_lt_f32_e32 vcc, s11, v107
	v_add_f32_e32 v76, v110, v76
	s_nop 0
	v_cndmask_b32_e32 v107, 0, v77, vcc
	v_sub_f32_e32 v77, v106, v101
	v_exp_f32_e32 v77, v77
	v_cmp_lt_f32_e32 vcc, s11, v106
	v_add_f32_e32 v76, v107, v76
	s_nop 0
	v_cndmask_b32_e32 v106, 0, v77, vcc
	v_sub_f32_e32 v77, v113, v101
	v_exp_f32_e32 v77, v77
	v_cmp_lt_f32_e32 vcc, s11, v113
	v_add_f32_e32 v76, v106, v76
	s_nop 0
	v_cndmask_b32_e32 v112, 0, v77, vcc
	v_sub_f32_e32 v77, v111, v101
	v_exp_f32_e32 v77, v77
	v_cmp_lt_f32_e32 vcc, s11, v111
	v_add_f32_e32 v76, v112, v76
	s_nop 0
	v_cndmask_b32_e32 v111, 0, v77, vcc
	v_sub_f32_e32 v77, v119, v101
	v_exp_f32_e32 v77, v77
	v_cmp_lt_f32_e32 vcc, s11, v119
	v_add_f32_e32 v76, v111, v76
	s_nop 0
	v_cndmask_b32_e32 v113, 0, v77, vcc
	v_sub_f32_e32 v77, v117, v101
	v_exp_f32_e32 v77, v77
	v_cmp_lt_f32_e32 vcc, s11, v117
	v_add_f32_e32 v76, v113, v76
	s_nop 0
	v_cndmask_b32_e32 v114, 0, v77, vcc
	v_add_f32_e32 v102, v114, v76
	v_cvt_pk_bf16_f32 v76, v58, v59
	v_add3_u32 v58, s31, v80, v99
	v_add_u32_e32 v66, 0x2000, v58
	ds_read2_b64 v[80:83], v66 offset0:128 offset1:130
	ds_read2_b64 v[84:87], v66 offset0:132 offset1:134
	v_cvt_pk_bf16_f32 v77, v60, v62
	v_add_u32_e32 v68, 0x3000, v58
	v_cvt_pk_bf16_f32 v58, v61, v63
	s_waitcnt lgkmcnt(1)
; #define MFMA32(a, b, c) __builtin_amdgcn_mfma_f32_32x32x16_bf16((a), (b), (c), 0, 0, 0)
; DI unsigned pack2(float a, float b) { f32x2_t v = {a, b}; bf16x2_t r = __builtin_convertvector(v, bf16x2_t); return __builtin_bit_cast(unsigned, r); }
; template <int NDT, int MODE, bool ALLON>
; DI void attn_tile(const bf16_t* Kl, int kst, const bf16_t* Vl, const bf16x8 (&q)[4], f32x16 (&O)[NDT], float& m, float& l,
;                   int kbase, int qp, int win, float cbias, const float* tab, bool lane_on) {
;     ...
;   l = l * alpha + psum;
;   if (__ballot(alpha != 1.f)) {
; #pragma unroll
;     for (int dt = 0; dt < NDT; ++dt)
; #pragma unroll
;       for (int i = 0; i < 16; ++i) O[dt][i] *= alpha;
;   }
; #pragma unroll
;   for (int st = 0; st < 2; ++st)
; #pragma unroll
;     for (int sk = 0; sk < 2; ++sk) {
;       u32x4 pu;
;       pu[0] = pack2(s[st][8 * sk + 0], s[st][8 * sk + 1]);
;       pu[1] = pack2(s[st][8 * sk + 2], s[st][8 * sk + 3]);
;       pu[2] = pack2(s[st][8 * sk + 4], s[st][8 * sk + 5]);
;       pu[3] = pack2(s[st][8 * sk + 6], s[st][8 * sk + 7]);
;       const bf16x8 pf = __builtin_bit_cast(bf16x8, pu);
; #pragma unroll
;       for (int dt = 0; dt < NDT; ++dt) {
;         const bf16_t* vp = Vl + (dt * 32 + lr) * 72 + st * 32 + sk * 16 + 4 * lh;
;         const uint2 v0 = *(const uint2*)(vp);
;         const uint2 v1 = *(const uint2*)(vp + 8);
;         u32x4 vu; vu[0] = v0.x; vu[1] = v0.y; vu[2] = v1.x; vu[3] = v1.y;
;         O[dt] = MFMA32(__builtin_bit_cast(bf16x8, vu), pf, O[dt]);
;       }
	v_mfma_f32_32x32x16_bf16 v[0:15], v[80:83], v[76:79], v[0:15]
	ds_read2_b64 v[80:83], v68 offset0:192 offset1:194
	v_cvt_pk_bf16_f32 v59, v65, v67
	ds_read2_b64 v[62:65], v68 offset0:196 offset1:198
	v_cvt_pk_bf16_f32 v60, v69, v71
	v_cvt_pk_bf16_f32 v61, v72, v73
	v_fmac_f32_e32 v102, v98, v90
	v_mov_b32_e32 v98, v102
	s_waitcnt lgkmcnt(1)
	v_mfma_f32_32x32x16_bf16 v[16:31], v[80:83], v[76:79], v[16:31]
	v_mov_b32_e32 v90, v101
	s_waitcnt lgkmcnt(0)
	v_mfma_f32_32x32x16_bf16 v[16:31], v[62:65], v[58:61], v[16:31]
	ds_read2_b64 v[62:65], v66 offset0:136 offset1:138
	v_mfma_f32_32x32x16_bf16 v[0:15], v[84:87], v[58:61], v[0:15]
	v_cvt_pk_bf16_f32 v58, v74, v75
	v_cvt_pk_bf16_f32 v59, v88, v89
	v_cvt_pk_bf16_f32 v60, v108, v104
	v_cvt_pk_bf16_f32 v61, v109, v103
	s_waitcnt lgkmcnt(0)
	s_nop 0
	v_mfma_f32_32x32x16_bf16 v[0:15], v[62:65], v[58:61], v[0:15]
	ds_read2_b64 v[62:65], v68 offset0:200 offset1:202
	s_waitcnt lgkmcnt(0)
	v_mfma_f32_32x32x16_bf16 v[16:31], v[62:65], v[58:61], v[16:31]
	ds_read2_b64 v[62:65], v66 offset0:140 offset1:142
	v_cvt_pk_bf16_f32 v58, v105, v110
	v_cvt_pk_bf16_f32 v59, v107, v106
	v_cvt_pk_bf16_f32 v60, v112, v111
	v_cvt_pk_bf16_f32 v61, v113, v114
	s_waitcnt lgkmcnt(0)
	s_nop 0
	v_mfma_f32_32x32x16_bf16 v[0:15], v[62:65], v[58:61], v[0:15]
	ds_read2_b64 v[62:65], v68 offset0:204 offset1:206
	s_waitcnt lgkmcnt(0)
	v_mfma_f32_32x32x16_bf16 v[16:31], v[62:65], v[58:61], v[16:31]
	s_nop 8
	v_mov_b32_e32 v69, v15
	v_mov_b32_e32 v68, v14
	v_mov_b32_e32 v73, v13
	v_mov_b32_e32 v72, v12
	v_mov_b32_e32 v77, v11
	v_mov_b32_e32 v76, v10
	v_mov_b32_e32 v81, v9
	v_mov_b32_e32 v59, v31
	v_mov_b32_e32 v58, v30
	v_mov_b32_e32 v61, v29
	v_mov_b32_e32 v60, v28
	v_mov_b32_e32 v63, v27
	v_mov_b32_e32 v62, v26
	v_mov_b32_e32 v65, v25
	v_mov_b32_e32 v64, v24
	v_mov_b32_e32 v67, v23
	v_mov_b32_e32 v66, v22
	v_mov_b32_e32 v71, v21
	v_mov_b32_e32 v70, v20
	v_mov_b32_e32 v75, v19
	v_mov_b32_e32 v74, v18
	v_mov_b32_e32 v79, v17
	v_mov_b32_e32 v78, v16
	v_mov_b32_e32 v80, v8
	v_mov_b32_e32 v83, v7
	v_mov_b32_e32 v82, v6
	v_mov_b32_e32 v85, v5
	v_mov_b32_e32 v84, v4
	v_mov_b32_e32 v89, v3
	v_mov_b32_e32 v88, v2
	v_mov_b32_e32 v87, v1
	v_mov_b32_e32 v86, v0
	s_branch .LBB0_899
; #define MFMA32(a, b, c) __builtin_amdgcn_mfma_f32_32x32x16_bf16((a), (b), (c), 0, 0, 0)
; DI unsigned pack2(float a, float b) { f32x2_t v = {a, b}; bf16x2_t r = __builtin_convertvector(v, bf16x2_t); return __builtin_bit_cast(unsigned, r); }
; DI float ex2(float x) { return __builtin_amdgcn_exp2f(x); }
; template <int NDT, int MODE, bool ALLON>
; DI void attn_tile(const bf16_t* Kl, int kst, const bf16_t* Vl, const bf16x8 (&q)[4], f32x16 (&O)[NDT], float& m, float& l,
;                   int kbase, int qp, int win, float cbias, const float* tab, bool lane_on) {
;     ...
; #pragma unroll
;     for (int st = 0; st < 2; ++st)
; #pragma unroll
;       for (int i = 0; i < 16; ++i) {
;         const float pe = s[st][i] > -5e29f ? ex2(s[st][i] - mn) : 0.f;
;         psum += pe;
;         s[st][i] = pe;
;       }
;   }
;   l = l * alpha + psum;
;   if (__ballot(alpha != 1.f)) {
; #pragma unroll
;     for (int dt = 0; dt < NDT; ++dt)
; #pragma unroll
;       for (int i = 0; i < 16; ++i) O[dt][i] *= alpha;
;   }
; #pragma unroll
;   for (int st = 0; st < 2; ++st)
; #pragma unroll
;     for (int sk = 0; sk < 2; ++sk) {
;       u32x4 pu;
;       pu[0] = pack2(s[st][8 * sk + 0], s[st][8 * sk + 1]);
;       pu[1] = pack2(s[st][8 * sk + 2], s[st][8 * sk + 3]);
;       pu[2] = pack2(s[st][8 * sk + 4], s[st][8 * sk + 5]);
;       pu[3] = pack2(s[st][8 * sk + 6], s[st][8 * sk + 7]);
;       const bf16x8 pf = __builtin_bit_cast(bf16x8, pu);
; #pragma unroll
;       for (int dt = 0; dt < NDT; ++dt) {
;         const bf16_t* vp = Vl + (dt * 32 + lr) * 72 + st * 32 + sk * 16 + 4 * lh;
;         const uint2 v0 = *(const uint2*)(vp);
;         const uint2 v1 = *(const uint2*)(vp + 8);
;         u32x4 vu; vu[0] = v0.x; vu[1] = v0.y; vu[2] = v1.x; vu[3] = v1.y;
;         O[dt] = MFMA32(__builtin_bit_cast(bf16x8, vu), pf, O[dt]);
;       }
.Lm1fast_2:
	v_sub_f32_e32 v58, v133, v101
	v_exp_f32_e32 v58, v58
	v_sub_f32_e32 v59, v131, v101
	v_exp_f32_e32 v59, v59
	v_sub_f32_e32 v62, v128, v101
	v_exp_f32_e32 v62, v62
	v_add_f32_e32 v60, 0, v58
	v_sub_f32_e32 v63, v130, v101
	v_add_f32_e32 v61, v59, v60
	v_sub_f32_e32 v60, v132, v101
	v_exp_f32_e32 v60, v60
	v_exp_f32_e32 v63, v63
	v_sub_f32_e32 v77, v115, v101
	v_exp_f32_e32 v77, v77
	v_add_f32_e32 v61, v60, v61
	v_lshlrev_b32_e32 v80, 1, v100
	v_add_f32_e32 v61, v62, v61
	s_nop 0
	v_mov_b32_e32 v64, v63
	v_sub_f32_e32 v63, v126, v101
	v_exp_f32_e32 v63, v63
	v_add_f32_e32 v61, v64, v61
	s_nop 0
	v_mov_b32_e32 v66, v63
	v_sub_f32_e32 v63, v129, v101
	v_exp_f32_e32 v63, v63
	v_add_f32_e32 v61, v66, v61
	v_cvt_pk_bf16_f32 v78, v64, v66
	v_mov_b32_e32 v68, v63
	v_sub_f32_e32 v63, v124, v101
	v_exp_f32_e32 v63, v63
	v_add_f32_e32 v61, v68, v61
	s_nop 0
	v_mov_b32_e32 v70, v63
	v_add_f32_e32 v63, v70, v61
	v_sub_f32_e32 v61, v127, v101
	v_exp_f32_e32 v61, v61
	v_cvt_pk_bf16_f32 v79, v68, v70
	s_nop 0
	v_add_f32_e32 v65, v61, v63
	v_sub_f32_e32 v63, v122, v101
	v_exp_f32_e32 v63, v63
	s_nop 1
	v_add_f32_e32 v67, v63, v65
	v_sub_f32_e32 v65, v125, v101
	v_exp_f32_e32 v65, v65
	s_nop 1
	v_add_f32_e32 v69, v65, v67
	v_sub_f32_e32 v67, v120, v101
	v_exp_f32_e32 v67, v67
	s_nop 1
	v_add_f32_e32 v71, v67, v69
	v_sub_f32_e32 v69, v123, v101
	v_exp_f32_e32 v69, v69
	s_nop 1
	v_add_f32_e32 v72, v69, v71
	v_sub_f32_e32 v71, v116, v101
	v_exp_f32_e32 v71, v71
	s_nop 1
	v_add_f32_e32 v73, v71, v72
	v_sub_f32_e32 v72, v121, v101
	v_exp_f32_e32 v72, v72
	s_nop 1
	v_add_f32_e32 v74, v72, v73
	v_sub_f32_e32 v73, v114, v101
	v_exp_f32_e32 v73, v73
	s_nop 1
	v_add_f32_e32 v75, v73, v74
	v_sub_f32_e32 v74, v118, v101
	v_exp_f32_e32 v74, v74
	s_nop 1
	v_add_f32_e32 v76, v74, v75
	v_sub_f32_e32 v75, v110, v101
	v_exp_f32_e32 v75, v75
	s_nop 1
	v_add_f32_e32 v76, v75, v76
	s_nop 0
	v_mov_b32_e32 v88, v77
	v_sub_f32_e32 v77, v108, v101
	v_exp_f32_e32 v77, v77
	v_add_f32_e32 v76, v88, v76
	s_nop 0
	v_mov_b32_e32 v89, v77
	v_sub_f32_e32 v77, v112, v101
	v_exp_f32_e32 v77, v77
	v_add_f32_e32 v76, v89, v76
	s_nop 0
	v_mov_b32_e32 v108, v77
	v_sub_f32_e32 v77, v104, v101
	v_exp_f32_e32 v77, v77
	v_add_f32_e32 v76, v108, v76
	s_nop 0
	v_mov_b32_e32 v104, v77
	v_sub_f32_e32 v77, v109, v101
	v_exp_f32_e32 v77, v77
	v_add_f32_e32 v76, v104, v76
	s_nop 0
	v_mov_b32_e32 v109, v77
	v_sub_f32_e32 v77, v103, v101
	v_exp_f32_e32 v77, v77
	v_add_f32_e32 v76, v109, v76
	s_nop 0
	v_mov_b32_e32 v103, v77
	v_sub_f32_e32 v77, v105, v101
	v_exp_f32_e32 v77, v77
	v_add_f32_e32 v76, v103, v76
	s_nop 0
	v_mov_b32_e32 v105, v77
	v_sub_f32_e32 v77, v102, v101
	v_exp_f32_e32 v77, v77
	v_add_f32_e32 v76, v105, v76
	s_nop 0
	v_mov_b32_e32 v110, v77
	v_sub_f32_e32 v77, v107, v101
	v_exp_f32_e32 v77, v77
	v_add_f32_e32 v76, v110, v76
	s_nop 0
	v_mov_b32_e32 v107, v77
	v_sub_f32_e32 v77, v106, v101
	v_exp_f32_e32 v77, v77
	v_add_f32_e32 v76, v107, v76
	s_nop 0
	v_mov_b32_e32 v106, v77
	v_sub_f32_e32 v77, v113, v101
	v_exp_f32_e32 v77, v77
	v_add_f32_e32 v76, v106, v76
	s_nop 0
	v_mov_b32_e32 v112, v77
	v_sub_f32_e32 v77, v111, v101
	v_exp_f32_e32 v77, v77
	v_add_f32_e32 v76, v112, v76
	s_nop 0
	v_mov_b32_e32 v111, v77
	v_sub_f32_e32 v77, v119, v101
	v_exp_f32_e32 v77, v77
	v_add_f32_e32 v76, v111, v76
	s_nop 0
	v_mov_b32_e32 v113, v77
	v_sub_f32_e32 v77, v117, v101
	v_exp_f32_e32 v77, v77
	v_add_f32_e32 v76, v113, v76
	s_nop 0
	v_mov_b32_e32 v114, v77
	v_add_f32_e32 v102, v114, v76
	v_cvt_pk_bf16_f32 v76, v58, v59
	v_add3_u32 v58, s31, v80, v99
	v_add_u32_e32 v66, 0x2000, v58
	ds_read2_b64 v[80:83], v66 offset0:128 offset1:130
	ds_read2_b64 v[84:87], v66 offset0:132 offset1:134
	v_cvt_pk_bf16_f32 v77, v60, v62
	v_add_u32_e32 v68, 0x3000, v58
	v_cvt_pk_bf16_f32 v58, v61, v63
	s_waitcnt lgkmcnt(1)
	v_mfma_f32_32x32x16_bf16 v[0:15], v[80:83], v[76:79], v[0:15]
	ds_read2_b64 v[80:83], v68 offset0:192 offset1:194
	v_cvt_pk_bf16_f32 v59, v65, v67
	ds_read2_b64 v[62:65], v68 offset0:196 offset1:198
	v_cvt_pk_bf16_f32 v60, v69, v71
	v_cvt_pk_bf16_f32 v61, v72, v73
	v_fmac_f32_e32 v102, v98, v90
	v_mov_b32_e32 v98, v102
	s_waitcnt lgkmcnt(1)
	v_mfma_f32_32x32x16_bf16 v[16:31], v[80:83], v[76:79], v[16:31]
	v_mov_b32_e32 v90, v101
	s_waitcnt lgkmcnt(0)
	v_mfma_f32_32x32x16_bf16 v[16:31], v[62:65], v[58:61], v[16:31]
	ds_read2_b64 v[62:65], v66 offset0:136 offset1:138
	v_mfma_f32_32x32x16_bf16 v[0:15], v[84:87], v[58:61], v[0:15]
	v_cvt_pk_bf16_f32 v58, v74, v75
	v_cvt_pk_bf16_f32 v59, v88, v89
	v_cvt_pk_bf16_f32 v60, v108, v104
	v_cvt_pk_bf16_f32 v61, v109, v103
	s_waitcnt lgkmcnt(0)
	s_nop 0
	v_mfma_f32_32x32x16_bf16 v[0:15], v[62:65], v[58:61], v[0:15]
	ds_read2_b64 v[62:65], v68 offset0:200 offset1:202
	s_waitcnt lgkmcnt(0)
	v_mfma_f32_32x32x16_bf16 v[16:31], v[62:65], v[58:61], v[16:31]
	ds_read2_b64 v[62:65], v66 offset0:140 offset1:142
	v_cvt_pk_bf16_f32 v58, v105, v110
	v_cvt_pk_bf16_f32 v59, v107, v106
	v_cvt_pk_bf16_f32 v60, v112, v111
	v_cvt_pk_bf16_f32 v61, v113, v114
	s_waitcnt lgkmcnt(0)
	s_nop 0
	v_mfma_f32_32x32x16_bf16 v[0:15], v[62:65], v[58:61], v[0:15]
	ds_read2_b64 v[62:65], v68 offset0:204 offset1:206
	s_waitcnt lgkmcnt(0)
	v_mfma_f32_32x32x16_bf16 v[16:31], v[62:65], v[58:61], v[16:31]
	s_nop 8
	v_mov_b32_e32 v69, v15
	v_mov_b32_e32 v68, v14
	v_mov_b32_e32 v73, v13
	v_mov_b32_e32 v72, v12
	v_mov_b32_e32 v77, v11
	v_mov_b32_e32 v76, v10
	v_mov_b32_e32 v81, v9
	v_mov_b32_e32 v59, v31
	v_mov_b32_e32 v58, v30
	v_mov_b32_e32 v61, v29
	v_mov_b32_e32 v60, v28
	v_mov_b32_e32 v63, v27
	v_mov_b32_e32 v62, v26
	v_mov_b32_e32 v65, v25
	v_mov_b32_e32 v64, v24
	v_mov_b32_e32 v67, v23
	v_mov_b32_e32 v66, v22
	v_mov_b32_e32 v71, v21
	v_mov_b32_e32 v70, v20
	v_mov_b32_e32 v75, v19
	v_mov_b32_e32 v74, v18
	v_mov_b32_e32 v79, v17
	v_mov_b32_e32 v78, v16
	v_mov_b32_e32 v80, v8
	v_mov_b32_e32 v83, v7
	v_mov_b32_e32 v82, v6
	v_mov_b32_e32 v85, v5
	v_mov_b32_e32 v84, v4
	v_mov_b32_e32 v89, v3
	v_mov_b32_e32 v88, v2
	v_mov_b32_e32 v87, v1
	v_mov_b32_e32 v86, v0

; #define MFMA32(a, b, c) __builtin_amdgcn_mfma_f32_32x32x16_bf16((a), (b), (c), 0, 0, 0)
; DI unsigned pack2(float a, float b) { f32x2_t v = {a, b}; bf16x2_t r = __builtin_convertvector(v, bf16x2_t); return __builtin_bit_cast(unsigned, r); }
; DI float ex2(float x) { return __builtin_amdgcn_exp2f(x); }
; template <int NDT, int MODE, bool ALLON>
; DI void attn_tile(const bf16_t* Kl, int kst, const bf16_t* Vl, const bf16x8 (&q)[4], f32x16 (&O)[NDT], float& m, float& l,
;                   int kbase, int qp, int win, float cbias, const float* tab, bool lane_on) {
;     ...
; #pragma unroll
;     for (int st = 0; st < 2; ++st)
; #pragma unroll
;       for (int i = 0; i < 16; ++i) {
;         const float pe = s[st][i] > -5e29f ? ex2(s[st][i] - mn) : 0.f;
;         psum += pe;
;         s[st][i] = pe;
;       }
;   }
;   l = l * alpha + psum;
;   if (__ballot(alpha != 1.f)) {
; #pragma unroll
;     for (int dt = 0; dt < NDT; ++dt)
; #pragma unroll
;       for (int i = 0; i < 16; ++i) O[dt][i] *= alpha;
;   }
; #pragma unroll
;   for (int st = 0; st < 2; ++st)
; #pragma unroll
;     for (int sk = 0; sk < 2; ++sk) {
;       u32x4 pu;
;       pu[0] = pack2(s[st][8 * sk + 0], s[st][8 * sk + 1]);
;       pu[1] = pack2(s[st][8 * sk + 2], s[st][8 * sk + 3]);
;       pu[2] = pack2(s[st][8 * sk + 4], s[st][8 * sk + 5]);
;       pu[3] = pack2(s[st][8 * sk + 6], s[st][8 * sk + 7]);
;       const bf16x8 pf = __builtin_bit_cast(bf16x8, pu);
; #pragma unroll
;       for (int dt = 0; dt < NDT; ++dt) {
;         const bf16_t* vp = Vl + (dt * 32 + lr) * 72 + st * 32 + sk * 16 + 4 * lh;
;         const uint2 v0 = *(const uint2*)(vp);
;         const uint2 v1 = *(const uint2*)(vp + 8);
;         u32x4 vu; vu[0] = v0.x; vu[1] = v0.y; vu[2] = v1.x; vu[3] = v1.y;
;         O[dt] = MFMA32(__builtin_bit_cast(bf16x8, vu), pf, O[dt]);
;       }
.LBB0_975:
	v_cmp_gt_f32_e32 vcc, s11, v150
	s_cbranch_vccz .Lm1fast_3
	v_sub_f32_e32 v74, v120, v150
	v_exp_f32_e32 v74, v74
	v_sub_f32_e32 v75, v116, v150
	v_exp_f32_e32 v75, v75
	v_cmp_lt_f32_e32 vcc, s11, v120
	s_nop 1
	v_cndmask_b32_e32 v76, 0, v74, vcc
	v_cmp_lt_f32_e32 vcc, s11, v116
	v_add_f32_e32 v74, 0, v76
	s_nop 0
	v_cndmask_b32_e32 v78, 0, v75, vcc
	v_sub_f32_e32 v75, v119, v150
	v_exp_f32_e32 v75, v75
	v_cmp_lt_f32_e32 vcc, s11, v119
	v_add_f32_e32 v74, v78, v74
	s_nop 0
	v_cndmask_b32_e32 v90, 0, v75, vcc
	v_sub_f32_e32 v75, v114, v150
	v_exp_f32_e32 v75, v75
	v_cmp_lt_f32_e32 vcc, s11, v114
	v_add_f32_e32 v74, v90, v74
	s_nop 0
	v_cndmask_b32_e32 v93, 0, v75, vcc
	v_sub_f32_e32 v75, v118, v150
	v_exp_f32_e32 v75, v75
	v_cmp_lt_f32_e32 vcc, s11, v118
	v_add_f32_e32 v74, v93, v74
	v_cvt_pk_bf16_f32 v118, v76, v78
	v_cndmask_b32_e32 v95, 0, v75, vcc
	v_sub_f32_e32 v75, v113, v150
	v_exp_f32_e32 v75, v75
	v_cmp_lt_f32_e32 vcc, s11, v113
	v_add_f32_e32 v74, v95, v74
	v_cvt_pk_bf16_f32 v119, v90, v93
	v_cndmask_b32_e32 v113, 0, v75, vcc
	v_sub_f32_e32 v75, v117, v150
	v_exp_f32_e32 v75, v75
	v_cmp_lt_f32_e32 vcc, s11, v117
	v_add_f32_e32 v74, v113, v74
	v_cvt_pk_bf16_f32 v120, v95, v113
	v_cndmask_b32_e32 v116, 0, v75, vcc
	v_sub_f32_e32 v75, v112, v150
	v_exp_f32_e32 v75, v75
	v_cmp_lt_f32_e32 vcc, s11, v112
	v_add_f32_e32 v74, v116, v74
	s_nop 0
	v_cndmask_b32_e32 v117, 0, v75, vcc
	v_add_f32_e32 v75, v117, v74
	v_sub_f32_e32 v74, v115, v150
	v_exp_f32_e32 v74, v74
	v_cmp_lt_f32_e32 vcc, s11, v115
	s_nop 1
	v_cndmask_b32_e32 v74, 0, v74, vcc
	v_add_f32_e32 v77, v74, v75
	v_sub_f32_e32 v75, v85, v150
	v_exp_f32_e32 v75, v75
	v_cmp_lt_f32_e32 vcc, s11, v85
	v_sub_f32_e32 v85, v87, v150
	v_exp_f32_e32 v85, v85
	v_cndmask_b32_e32 v75, 0, v75, vcc
	v_add_f32_e32 v79, v75, v77
	v_sub_f32_e32 v77, v88, v150
	v_exp_f32_e32 v77, v77
	v_cmp_lt_f32_e32 vcc, s11, v88
	s_nop 1
	v_cndmask_b32_e32 v77, 0, v77, vcc
	v_cmp_lt_f32_e32 vcc, s11, v83
	v_sub_f32_e32 v83, v83, v150
	v_exp_f32_e32 v83, v83
	v_add_f32_e32 v79, v77, v79
	v_cndmask_b32_e32 v83, 0, v83, vcc
	v_cmp_lt_f32_e32 vcc, s11, v87
	v_add_f32_e32 v79, v83, v79
	s_nop 0
	v_cndmask_b32_e32 v85, 0, v85, vcc
	v_cmp_lt_f32_e32 vcc, s11, v81
	v_sub_f32_e32 v81, v81, v150
	v_exp_f32_e32 v81, v81
	v_add_f32_e32 v79, v85, v79
	v_cndmask_b32_e32 v94, 0, v81, vcc
	v_sub_f32_e32 v81, v86, v150
	v_exp_f32_e32 v81, v81
	v_cmp_lt_f32_e32 vcc, s11, v86
	v_add_f32_e32 v79, v94, v79
	s_nop 0
	v_cndmask_b32_e32 v112, 0, v81, vcc
	v_cmp_lt_f32_e32 vcc, s11, v80
	v_sub_f32_e32 v80, v80, v150
	v_exp_f32_e32 v80, v80
	v_add_f32_e32 v79, v112, v79
	v_cndmask_b32_e32 v114, 0, v80, vcc
	v_add_f32_e32 v80, v114, v79
	v_sub_f32_e32 v79, v84, v150
	v_exp_f32_e32 v79, v79
	v_cmp_lt_f32_e32 vcc, s11, v84
	s_nop 1
	v_cndmask_b32_e32 v79, 0, v79, vcc
	v_add_f32_e32 v81, v79, v80
	v_sub_f32_e32 v80, v82, v150
	v_exp_f32_e32 v80, v80
	v_cmp_lt_f32_e32 vcc, s11, v82
	s_nop 1
	v_cndmask_b32_e32 v80, 0, v80, vcc
	v_add_f32_e32 v82, v80, v81
	v_sub_f32_e32 v81, v89, v150
	v_exp_f32_e32 v81, v81
	v_cmp_lt_f32_e32 vcc, s11, v89
	v_mul_u32_u24_e32 v89, 0x48, v152
	v_lshlrev_b32_e32 v76, 1, v89
	v_cndmask_b32_e32 v81, 0, v81, vcc
	v_cmp_lt_f32_e32 vcc, s11, v65
	v_sub_f32_e32 v65, v65, v150
	v_exp_f32_e32 v65, v65
	v_add_f32_e32 v84, v81, v82
	v_cvt_pk_bf16_f32 v80, v79, v80
	v_cndmask_b32_e32 v82, 0, v65, vcc
	v_cmp_lt_f32_e32 vcc, s11, v67
	v_sub_f32_e32 v67, v67, v150
	v_exp_f32_e32 v67, v67
	v_add_f32_e32 v65, v82, v84
	v_cvt_pk_bf16_f32 v81, v81, v82
	v_cndmask_b32_e32 v84, 0, v67, vcc
	v_cmp_lt_f32_e32 vcc, s11, v66
	v_sub_f32_e32 v66, v66, v150
	v_exp_f32_e32 v66, v66
	v_add_f32_e32 v65, v84, v65
	v_cndmask_b32_e32 v86, 0, v66, vcc
	v_sub_f32_e32 v66, v69, v150
	v_exp_f32_e32 v66, v66
	v_cmp_lt_f32_e32 vcc, s11, v69
	v_add_f32_e32 v65, v86, v65
	v_sub_f32_e32 v69, v72, v150
	v_cndmask_b32_e32 v87, 0, v66, vcc
	v_sub_f32_e32 v66, v68, v150
	v_exp_f32_e32 v66, v66
	v_cmp_lt_f32_e32 vcc, s11, v68
	v_add_f32_e32 v65, v87, v65
	v_exp_f32_e32 v69, v69
	v_cndmask_b32_e32 v88, 0, v66, vcc
	v_add_f32_e32 v66, v88, v65
	v_sub_f32_e32 v65, v71, v150
	v_exp_f32_e32 v65, v65
	v_cmp_lt_f32_e32 vcc, s11, v71
	v_sub_f32_e32 v71, v91, v150
	v_exp_f32_e32 v71, v71
	v_cndmask_b32_e32 v65, 0, v65, vcc
	v_add_f32_e32 v67, v65, v66
	v_sub_f32_e32 v66, v70, v150
	v_exp_f32_e32 v66, v66
	v_cmp_lt_f32_e32 vcc, s11, v70
	v_sub_f32_e32 v70, v92, v150
	v_exp_f32_e32 v70, v70
	v_cndmask_b32_e32 v66, 0, v66, vcc
	v_add_f32_e32 v68, v66, v67
	v_sub_f32_e32 v67, v73, v150
	v_exp_f32_e32 v67, v67
	v_cmp_lt_f32_e32 vcc, s11, v73
	v_sub_f32_e32 v73, v121, v150
	v_exp_f32_e32 v73, v73
	v_cndmask_b32_e32 v67, 0, v67, vcc
	v_cmp_lt_f32_e32 vcc, s11, v72
	v_sub_f32_e32 v72, v122, v150
	v_exp_f32_e32 v72, v72
	v_add_f32_e32 v68, v67, v68
	v_cndmask_b32_e32 v69, 0, v69, vcc
	v_cmp_lt_f32_e32 vcc, s11, v92
	v_add_f32_e32 v68, v69, v68
	v_cvt_pk_bf16_f32 v82, v84, v86
	v_cndmask_b32_e32 v70, 0, v70, vcc
	v_cmp_lt_f32_e32 vcc, s11, v91
	v_add_f32_e32 v68, v70, v68
	s_nop 0
	v_cndmask_b32_e32 v71, 0, v71, vcc
	v_cmp_lt_f32_e32 vcc, s11, v122
	v_add_f32_e32 v68, v71, v68
	s_nop 0
	v_cndmask_b32_e32 v72, 0, v72, vcc
	v_cmp_lt_f32_e32 vcc, s11, v121
	v_add_f32_e32 v68, v72, v68
	v_cvt_pk_bf16_f32 v121, v116, v117
	v_cndmask_b32_e32 v73, 0, v73, vcc
	v_add_f32_e32 v68, v73, v68
	v_fmac_f32_e32 v68, v151, v64
	v_lshlrev_b32_e32 v64, 3, v153
	v_add3_u32 v76, s9, v64, v76
	v_add_u32_e32 v64, 0x4000, v76
	ds_read2_b64 v[90:93], v64 offset0:128 offset1:130
	ds_read2_b64 v[152:155], v64 offset0:132 offset1:134
	v_add_u32_e32 v78, 0x5000, v76
	s_waitcnt lgkmcnt(1)
; #define MFMA32(a, b, c) __builtin_amdgcn_mfma_f32_32x32x16_bf16((a), (b), (c), 0, 0, 0)
; DI unsigned pack2(float a, float b) { f32x2_t v = {a, b}; bf16x2_t r = __builtin_convertvector(v, bf16x2_t); return __builtin_bit_cast(unsigned, r); }
; template <int NDT, int MODE, bool ALLON>
; DI void attn_tile(const bf16_t* Kl, int kst, const bf16_t* Vl, const bf16x8 (&q)[4], f32x16 (&O)[NDT], float& m, float& l,
;                   int kbase, int qp, int win, float cbias, const float* tab, bool lane_on) {
;     ...
; #pragma unroll
;   for (int st = 0; st < 2; ++st)
; #pragma unroll
;     for (int sk = 0; sk < 2; ++sk) {
;       u32x4 pu;
;       pu[0] = pack2(s[st][8 * sk + 0], s[st][8 * sk + 1]);
;       pu[1] = pack2(s[st][8 * sk + 2], s[st][8 * sk + 3]);
;       pu[2] = pack2(s[st][8 * sk + 4], s[st][8 * sk + 5]);
;       pu[3] = pack2(s[st][8 * sk + 6], s[st][8 * sk + 7]);
;       const bf16x8 pf = __builtin_bit_cast(bf16x8, pu);
; #pragma unroll
;       for (int dt = 0; dt < NDT; ++dt) {
;         const bf16_t* vp = Vl + (dt * 32 + lr) * 72 + st * 32 + sk * 16 + 4 * lh;
;         const uint2 v0 = *(const uint2*)(vp);
;         const uint2 v1 = *(const uint2*)(vp + 8);
;         u32x4 vu; vu[0] = v0.x; vu[1] = v0.y; vu[2] = v1.x; vu[3] = v1.y;
;         O[dt] = MFMA32(__builtin_bit_cast(bf16x8, vu), pf, O[dt]);
;       }
	v_mfma_f32_32x32x16_bf16 v[48:63], v[90:93], v[118:121], v[48:63]
	ds_read2_b64 v[90:93], v78 offset0:192 offset1:194
	v_add_u32_e32 v89, 0x6800, v76
	v_add_u32_e32 v76, 0x7800, v76
	s_waitcnt lgkmcnt(0)
	v_mfma_f32_32x32x16_bf16 v[32:47], v[90:93], v[118:121], v[32:47]
	ds_read2_b64 v[90:93], v89 offset1:2
	s_waitcnt lgkmcnt(0)
	v_mfma_f32_32x32x16_bf16 v[16:31], v[90:93], v[118:121], v[16:31]
	ds_read2_b64 v[90:93], v76 offset0:64 offset1:66
	s_waitcnt lgkmcnt(0)
	v_mfma_f32_32x32x16_bf16 v[0:15], v[90:93], v[118:121], v[0:15]
	v_cvt_pk_bf16_f32 v90, v74, v75
	v_cvt_pk_bf16_f32 v91, v77, v83
	v_cvt_pk_bf16_f32 v92, v85, v94
	v_cvt_pk_bf16_f32 v93, v112, v114
	v_cvt_pk_bf16_f32 v83, v87, v88
	ds_read2_b64 v[84:87], v64 offset0:136 offset1:138
	ds_read2_b64 v[112:115], v78 offset0:196 offset1:198
	v_mfma_f32_32x32x16_bf16 v[48:63], v[152:155], v[90:93], v[48:63]
	s_waitcnt lgkmcnt(1)
	v_mfma_f32_32x32x16_bf16 v[48:63], v[84:87], v[80:83], v[48:63]
	ds_read2_b64 v[84:87], v78 offset0:200 offset1:202
	s_waitcnt lgkmcnt(1)
	v_mfma_f32_32x32x16_bf16 v[32:47], v[112:115], v[90:93], v[32:47]
	ds_read2_b64 v[112:115], v89 offset0:4 offset1:6
	s_waitcnt lgkmcnt(1)
	v_mfma_f32_32x32x16_bf16 v[32:47], v[84:87], v[80:83], v[32:47]
	ds_read2_b64 v[84:87], v89 offset0:8 offset1:10
	s_waitcnt lgkmcnt(1)
	v_mfma_f32_32x32x16_bf16 v[16:31], v[112:115], v[90:93], v[16:31]
	ds_read2_b64 v[112:115], v76 offset0:68 offset1:70
	s_waitcnt lgkmcnt(1)
	v_mfma_f32_32x32x16_bf16 v[16:31], v[84:87], v[80:83], v[16:31]
	ds_read2_b64 v[84:87], v76 offset0:72 offset1:74
	s_waitcnt lgkmcnt(1)
	v_mfma_f32_32x32x16_bf16 v[0:15], v[112:115], v[90:93], v[0:15]
	s_waitcnt lgkmcnt(0)
	v_mfma_f32_32x32x16_bf16 v[0:15], v[84:87], v[80:83], v[0:15]
	v_cvt_pk_bf16_f32 v80, v65, v66
	v_cvt_pk_bf16_f32 v81, v67, v69
	ds_read2_b64 v[64:67], v64 offset0:140 offset1:142
	v_cvt_pk_bf16_f32 v82, v70, v71
	v_cvt_pk_bf16_f32 v83, v72, v73
	s_waitcnt lgkmcnt(0)
	s_nop 0
	v_mfma_f32_32x32x16_bf16 v[48:63], v[64:67], v[80:83], v[48:63]
	ds_read2_b64 v[64:67], v78 offset0:204 offset1:206
	s_waitcnt lgkmcnt(0)
	v_mfma_f32_32x32x16_bf16 v[32:47], v[64:67], v[80:83], v[32:47]
	ds_read2_b64 v[64:67], v89 offset0:12 offset1:14
	s_waitcnt lgkmcnt(0)
	v_mfma_f32_32x32x16_bf16 v[16:31], v[64:67], v[80:83], v[16:31]
	ds_read2_b64 v[64:67], v76 offset0:76 offset1:78
	s_waitcnt lgkmcnt(0)
	v_mfma_f32_32x32x16_bf16 v[0:15], v[64:67], v[80:83], v[0:15]
	s_branch .LBB0_976
; #define MFMA32(a, b, c) __builtin_amdgcn_mfma_f32_32x32x16_bf16((a), (b), (c), 0, 0, 0)
; DI unsigned pack2(float a, float b) { f32x2_t v = {a, b}; bf16x2_t r = __builtin_convertvector(v, bf16x2_t); return __builtin_bit_cast(unsigned, r); }
; DI float ex2(float x) { return __builtin_amdgcn_exp2f(x); }
; template <int NDT, int MODE, bool ALLON>
; DI void attn_tile(const bf16_t* Kl, int kst, const bf16_t* Vl, const bf16x8 (&q)[4], f32x16 (&O)[NDT], float& m, float& l,
;                   int kbase, int qp, int win, float cbias, const float* tab, bool lane_on) {
;     ...
; #pragma unroll
;     for (int st = 0; st < 2; ++st)
; #pragma unroll
;       for (int i = 0; i < 16; ++i) {
;         const float pe = s[st][i] > -5e29f ? ex2(s[st][i] - mn) : 0.f;
;         psum += pe;
;         s[st][i] = pe;
;       }
;   }
;   l = l * alpha + psum;
;   if (__ballot(alpha != 1.f)) {
; #pragma unroll
;     for (int dt = 0; dt < NDT; ++dt)
; #pragma unroll
;       for (int i = 0; i < 16; ++i) O[dt][i] *= alpha;
;   }
; #pragma unroll
;   for (int st = 0; st < 2; ++st)
; #pragma unroll
;     for (int sk = 0; sk < 2; ++sk) {
;       u32x4 pu;
;       pu[0] = pack2(s[st][8 * sk + 0], s[st][8 * sk + 1]);
;       pu[1] = pack2(s[st][8 * sk + 2], s[st][8 * sk + 3]);
;       pu[2] = pack2(s[st][8 * sk + 4], s[st][8 * sk + 5]);
;       pu[3] = pack2(s[st][8 * sk + 6], s[st][8 * sk + 7]);
;       const bf16x8 pf = __builtin_bit_cast(bf16x8, pu);
; #pragma unroll
;       for (int dt = 0; dt < NDT; ++dt) {
;         const bf16_t* vp = Vl + (dt * 32 + lr) * 72 + st * 32 + sk * 16 + 4 * lh;
;         const uint2 v0 = *(const uint2*)(vp);
;         const uint2 v1 = *(const uint2*)(vp + 8);
;         u32x4 vu; vu[0] = v0.x; vu[1] = v0.y; vu[2] = v1.x; vu[3] = v1.y;
;         O[dt] = MFMA32(__builtin_bit_cast(bf16x8, vu), pf, O[dt]);
;       }
.Lm1fast_3:
	v_sub_f32_e32 v74, v120, v150
	v_exp_f32_e32 v74, v74
	v_sub_f32_e32 v75, v116, v150
	v_exp_f32_e32 v75, v75
	s_nop 1
	v_mov_b32_e32 v76, v74
	v_add_f32_e32 v74, 0, v76
	s_nop 0
	v_mov_b32_e32 v78, v75
	v_sub_f32_e32 v75, v119, v150
	v_exp_f32_e32 v75, v75
	v_add_f32_e32 v74, v78, v74
	s_nop 0
	v_mov_b32_e32 v90, v75
	v_sub_f32_e32 v75, v114, v150
	v_exp_f32_e32 v75, v75
	v_add_f32_e32 v74, v90, v74
	s_nop 0
	v_mov_b32_e32 v93, v75
	v_sub_f32_e32 v75, v118, v150
	v_exp_f32_e32 v75, v75
	v_add_f32_e32 v74, v93, v74
	v_cvt_pk_bf16_f32 v118, v76, v78
	v_mov_b32_e32 v95, v75
	v_sub_f32_e32 v75, v113, v150
	v_exp_f32_e32 v75, v75
	v_add_f32_e32 v74, v95, v74
	v_cvt_pk_bf16_f32 v119, v90, v93
	v_mov_b32_e32 v113, v75
	v_sub_f32_e32 v75, v117, v150
	v_exp_f32_e32 v75, v75
	v_add_f32_e32 v74, v113, v74
	v_cvt_pk_bf16_f32 v120, v95, v113
	v_mov_b32_e32 v116, v75
	v_sub_f32_e32 v75, v112, v150
	v_exp_f32_e32 v75, v75
	v_add_f32_e32 v74, v116, v74
	s_nop 0
	v_mov_b32_e32 v117, v75
	v_add_f32_e32 v75, v117, v74
	v_sub_f32_e32 v74, v115, v150
	v_exp_f32_e32 v74, v74
	s_nop 1
	v_add_f32_e32 v77, v74, v75
	v_sub_f32_e32 v75, v85, v150
	v_exp_f32_e32 v75, v75
	v_sub_f32_e32 v85, v87, v150
	v_exp_f32_e32 v85, v85
	v_add_f32_e32 v79, v75, v77
	v_sub_f32_e32 v77, v88, v150
	v_exp_f32_e32 v77, v77
	s_nop 1
	v_sub_f32_e32 v83, v83, v150
	v_exp_f32_e32 v83, v83
	v_add_f32_e32 v79, v77, v79
	v_add_f32_e32 v79, v83, v79
	s_nop 0
	v_sub_f32_e32 v81, v81, v150
	v_exp_f32_e32 v81, v81
	v_add_f32_e32 v79, v85, v79
	v_mov_b32_e32 v94, v81
	v_sub_f32_e32 v81, v86, v150
	v_exp_f32_e32 v81, v81
	v_add_f32_e32 v79, v94, v79
	s_nop 0
	v_mov_b32_e32 v112, v81
	v_sub_f32_e32 v80, v80, v150
	v_exp_f32_e32 v80, v80
	v_add_f32_e32 v79, v112, v79
	v_mov_b32_e32 v114, v80
	v_add_f32_e32 v80, v114, v79
	v_sub_f32_e32 v79, v84, v150
	v_exp_f32_e32 v79, v79
	s_nop 1
	v_add_f32_e32 v81, v79, v80
	v_sub_f32_e32 v80, v82, v150
	v_exp_f32_e32 v80, v80
	s_nop 1
	v_add_f32_e32 v82, v80, v81
	v_sub_f32_e32 v81, v89, v150
	v_exp_f32_e32 v81, v81
	v_mul_u32_u24_e32 v89, 0x48, v152
	v_lshlrev_b32_e32 v76, 1, v89
	v_sub_f32_e32 v65, v65, v150
	v_exp_f32_e32 v65, v65
	v_add_f32_e32 v84, v81, v82
	v_cvt_pk_bf16_f32 v80, v79, v80
	v_mov_b32_e32 v82, v65
	v_sub_f32_e32 v67, v67, v150
	v_exp_f32_e32 v67, v67
	v_add_f32_e32 v65, v82, v84
	v_cvt_pk_bf16_f32 v81, v81, v82
	v_mov_b32_e32 v84, v67
	v_sub_f32_e32 v66, v66, v150
	v_exp_f32_e32 v66, v66
	v_add_f32_e32 v65, v84, v65
	v_mov_b32_e32 v86, v66
	v_sub_f32_e32 v66, v69, v150
	v_exp_f32_e32 v66, v66
	v_add_f32_e32 v65, v86, v65
	v_sub_f32_e32 v69, v72, v150
	v_mov_b32_e32 v87, v66
	v_sub_f32_e32 v66, v68, v150
	v_exp_f32_e32 v66, v66
	v_add_f32_e32 v65, v87, v65
	v_exp_f32_e32 v69, v69
	v_mov_b32_e32 v88, v66
	v_add_f32_e32 v66, v88, v65
	v_sub_f32_e32 v65, v71, v150
	v_exp_f32_e32 v65, v65
	v_sub_f32_e32 v71, v91, v150
	v_exp_f32_e32 v71, v71
	v_add_f32_e32 v67, v65, v66
	v_sub_f32_e32 v66, v70, v150
	v_exp_f32_e32 v66, v66
	v_sub_f32_e32 v70, v92, v150
	v_exp_f32_e32 v70, v70
	v_add_f32_e32 v68, v66, v67
	v_sub_f32_e32 v67, v73, v150
	v_exp_f32_e32 v67, v67
	v_sub_f32_e32 v73, v121, v150
	v_exp_f32_e32 v73, v73
	v_sub_f32_e32 v72, v122, v150
	v_exp_f32_e32 v72, v72
	v_add_f32_e32 v68, v67, v68
	v_add_f32_e32 v68, v69, v68
	v_cvt_pk_bf16_f32 v82, v84, v86
	v_add_f32_e32 v68, v70, v68
	s_nop 0
	v_add_f32_e32 v68, v71, v68
	s_nop 0
	v_add_f32_e32 v68, v72, v68
	v_cvt_pk_bf16_f32 v121, v116, v117
	v_add_f32_e32 v68, v73, v68
	v_fmac_f32_e32 v68, v151, v64
	v_lshlrev_b32_e32 v64, 3, v153
	v_add3_u32 v76, s9, v64, v76
	v_add_u32_e32 v64, 0x4000, v76
	ds_read2_b64 v[90:93], v64 offset0:128 offset1:130
	ds_read2_b64 v[152:155], v64 offset0:132 offset1:134
	v_add_u32_e32 v78, 0x5000, v76
	s_waitcnt lgkmcnt(1)
	v_mfma_f32_32x32x16_bf16 v[48:63], v[90:93], v[118:121], v[48:63]
	ds_read2_b64 v[90:93], v78 offset0:192 offset1:194
	v_add_u32_e32 v89, 0x6800, v76
	v_add_u32_e32 v76, 0x7800, v76
	s_waitcnt lgkmcnt(0)
	v_mfma_f32_32x32x16_bf16 v[32:47], v[90:93], v[118:121], v[32:47]
	ds_read2_b64 v[90:93], v89 offset1:2
	s_waitcnt lgkmcnt(0)
	v_mfma_f32_32x32x16_bf16 v[16:31], v[90:93], v[118:121], v[16:31]
	ds_read2_b64 v[90:93], v76 offset0:64 offset1:66
	s_waitcnt lgkmcnt(0)
	v_mfma_f32_32x32x16_bf16 v[0:15], v[90:93], v[118:121], v[0:15]
	v_cvt_pk_bf16_f32 v90, v74, v75
	v_cvt_pk_bf16_f32 v91, v77, v83
	v_cvt_pk_bf16_f32 v92, v85, v94
	v_cvt_pk_bf16_f32 v93, v112, v114
	v_cvt_pk_bf16_f32 v83, v87, v88
	ds_read2_b64 v[84:87], v64 offset0:136 offset1:138
	ds_read2_b64 v[112:115], v78 offset0:196 offset1:198
	v_mfma_f32_32x32x16_bf16 v[48:63], v[152:155], v[90:93], v[48:63]
	s_waitcnt lgkmcnt(1)
	v_mfma_f32_32x32x16_bf16 v[48:63], v[84:87], v[80:83], v[48:63]
	ds_read2_b64 v[84:87], v78 offset0:200 offset1:202
	s_waitcnt lgkmcnt(1)
	v_mfma_f32_32x32x16_bf16 v[32:47], v[112:115], v[90:93], v[32:47]
	ds_read2_b64 v[112:115], v89 offset0:4 offset1:6
	s_waitcnt lgkmcnt(1)
	v_mfma_f32_32x32x16_bf16 v[32:47], v[84:87], v[80:83], v[32:47]
	ds_read2_b64 v[84:87], v89 offset0:8 offset1:10
	s_waitcnt lgkmcnt(1)
	v_mfma_f32_32x32x16_bf16 v[16:31], v[112:115], v[90:93], v[16:31]
	ds_read2_b64 v[112:115], v76 offset0:68 offset1:70
	s_waitcnt lgkmcnt(1)
	v_mfma_f32_32x32x16_bf16 v[16:31], v[84:87], v[80:83], v[16:31]
	ds_read2_b64 v[84:87], v76 offset0:72 offset1:74
	s_waitcnt lgkmcnt(1)
	v_mfma_f32_32x32x16_bf16 v[0:15], v[112:115], v[90:93], v[0:15]
	s_waitcnt lgkmcnt(0)
	v_mfma_f32_32x32x16_bf16 v[0:15], v[84:87], v[80:83], v[0:15]
	v_cvt_pk_bf16_f32 v80, v65, v66
	v_cvt_pk_bf16_f32 v81, v67, v69
	ds_read2_b64 v[64:67], v64 offset0:140 offset1:142
	v_cvt_pk_bf16_f32 v82, v70, v71
	v_cvt_pk_bf16_f32 v83, v72, v73
	s_waitcnt lgkmcnt(0)
	s_nop 0
	v_mfma_f32_32x32x16_bf16 v[48:63], v[64:67], v[80:83], v[48:63]
	ds_read2_b64 v[64:67], v78 offset0:204 offset1:206
	s_waitcnt lgkmcnt(0)
	v_mfma_f32_32x32x16_bf16 v[32:47], v[64:67], v[80:83], v[32:47]
	ds_read2_b64 v[64:67], v89 offset0:12 offset1:14
	s_waitcnt lgkmcnt(0)
	v_mfma_f32_32x32x16_bf16 v[16:31], v[64:67], v[80:83], v[16:31]
	ds_read2_b64 v[64:67], v76 offset0:76 offset1:78
	s_waitcnt lgkmcnt(0)
	v_mfma_f32_32x32x16_bf16 v[0:15], v[64:67], v[80:83], v[0:15]
